# speedup vs baseline: 1.1393x; 1.0023x over previous
.LBB0_197:
	v_accvgpr_read_b32 v216, a205
	v_accvgpr_write_b32 a192, v128
	v_mov_b32_e32 v217, v128
	v_mov_b32_e32 v128, 0
	v_accvgpr_read_b32 v64, a64
	v_mov_b32_e32 v129, v128
	v_mov_b32_e32 v130, v128
	v_mov_b32_e32 v131, v128
	v_accvgpr_read_b32 v65, a65
	v_accvgpr_read_b32 v66, a66
	v_accvgpr_read_b32 v67, a67
	v_accvgpr_read_b32 v68, a68
	v_accvgpr_read_b32 v69, a69
	v_accvgpr_read_b32 v70, a70
	v_accvgpr_read_b32 v71, a71
	v_accvgpr_read_b32 v72, a72
	v_accvgpr_read_b32 v73, a73
	v_accvgpr_read_b32 v74, a74
	v_accvgpr_read_b32 v75, a75
	v_accvgpr_read_b32 v76, a76
	v_accvgpr_read_b32 v77, a77
	v_accvgpr_read_b32 v78, a78
	v_accvgpr_read_b32 v79, a79
	v_mfma_f32_32x32x16_bf16 a[64:79], v[128:131], v[128:131], 0
	v_mov_b32_e32 v128, 0
	v_accvgpr_read_b32 v63, a47
	v_mov_b32_e32 v129, v128
	v_mov_b32_e32 v130, v128
	v_mov_b32_e32 v131, v128
	v_accvgpr_read_b32 v62, a46
	v_accvgpr_read_b32 v61, a45
	v_accvgpr_read_b32 v60, a44
	v_accvgpr_read_b32 v59, a43
	v_accvgpr_read_b32 v58, a42
	v_accvgpr_read_b32 v57, a41
	v_accvgpr_read_b32 v56, a40
	v_accvgpr_read_b32 v55, a39
	v_accvgpr_read_b32 v54, a38
	v_accvgpr_read_b32 v53, a37
	v_accvgpr_read_b32 v52, a36
	v_accvgpr_read_b32 v51, a35
	v_accvgpr_read_b32 v50, a34
	v_accvgpr_read_b32 v49, a33
	v_accvgpr_read_b32 v48, a32
	v_mfma_f32_32x32x16_bf16 a[32:47], v[128:131], v[128:131], 0
	v_mov_b32_e32 v128, 0
	v_accvgpr_read_b32 v32, a80
	v_mov_b32_e32 v129, v128
	v_mov_b32_e32 v130, v128
	v_mov_b32_e32 v131, v128
	v_accvgpr_read_b32 v33, a81
	v_accvgpr_read_b32 v34, a82
	v_accvgpr_read_b32 v35, a83
	v_accvgpr_read_b32 v36, a84
	v_accvgpr_read_b32 v37, a85
	v_accvgpr_read_b32 v38, a86
	v_accvgpr_read_b32 v39, a87
	v_accvgpr_read_b32 v40, a88
	v_accvgpr_read_b32 v41, a89
	v_accvgpr_read_b32 v42, a90
	v_accvgpr_read_b32 v43, a91
	v_accvgpr_read_b32 v44, a92
	v_accvgpr_read_b32 v45, a93
	v_accvgpr_read_b32 v46, a94
	v_accvgpr_read_b32 v47, a95
	v_mfma_f32_32x32x16_bf16 a[80:95], v[128:131], v[128:131], 0
	v_mov_b32_e32 v128, 0
	v_accvgpr_read_b32 v95, a15
	v_mov_b32_e32 v129, v128
	v_mov_b32_e32 v130, v128
	v_mov_b32_e32 v131, v128
	v_accvgpr_read_b32 v94, a14
	v_accvgpr_read_b32 v93, a13
	v_accvgpr_read_b32 v92, a12
	v_accvgpr_read_b32 v91, a11
	v_accvgpr_read_b32 v90, a10
	v_accvgpr_read_b32 v89, a9
	v_accvgpr_read_b32 v88, a8
	v_accvgpr_read_b32 v87, a7
	v_accvgpr_read_b32 v86, a6
	v_accvgpr_read_b32 v85, a5
	v_accvgpr_read_b32 v84, a4
	v_accvgpr_read_b32 v83, a3
	v_accvgpr_read_b32 v82, a2
	v_accvgpr_read_b32 v81, a1
	v_accvgpr_read_b32 v80, a0
	v_mfma_f32_32x32x16_bf16 a[0:15], v[128:131], v[128:131], 0
	v_mov_b32_e32 v128, 0
	v_accvgpr_read_b32 v16, a96
	v_mov_b32_e32 v129, v128
	v_mov_b32_e32 v130, v128
	v_mov_b32_e32 v131, v128
	v_accvgpr_read_b32 v17, a97
	v_accvgpr_read_b32 v18, a98
	v_accvgpr_read_b32 v19, a99
	v_accvgpr_read_b32 v20, a100
	v_accvgpr_read_b32 v21, a101
	v_accvgpr_read_b32 v22, a102
	v_accvgpr_read_b32 v23, a103
	v_accvgpr_read_b32 v24, a104
	v_accvgpr_read_b32 v25, a105
	v_accvgpr_read_b32 v26, a106
	v_accvgpr_read_b32 v27, a107
	v_accvgpr_read_b32 v28, a108
	v_accvgpr_read_b32 v29, a109
	v_accvgpr_read_b32 v30, a110
	v_accvgpr_read_b32 v31, a111
	v_mfma_f32_32x32x16_bf16 a[96:111], v[128:131], v[128:131], 0
	v_mov_b32_e32 v128, 0
	v_lshl_add_u64 v[156:157], v[132:133], 0, s[96:97]
	v_mov_b32_e32 v129, v128
	v_mov_b32_e32 v130, v128
	v_mov_b32_e32 v131, v128
	s_mov_b32 s0, 0x16100000
	v_add_co_u32_e64 v160, s[0:1], s0, v156
	v_accvgpr_read_b32 v127, a31
	s_nop 0
	v_addc_co_u32_e64 v161, s[0:1], 0, v157, s[0:1]
	s_mov_b32 s0, 0x16110000
	v_accvgpr_read_b32 v126, a30
	v_accvgpr_read_b32 v125, a29
	v_accvgpr_read_b32 v124, a28
	v_accvgpr_read_b32 v123, a27
	v_accvgpr_read_b32 v122, a26
	v_accvgpr_read_b32 v121, a25
	v_accvgpr_read_b32 v120, a24
	v_accvgpr_read_b32 v119, a23
	v_accvgpr_read_b32 v118, a22
	v_accvgpr_read_b32 v117, a21
	v_accvgpr_read_b32 v116, a20
	v_accvgpr_read_b32 v115, a19
	v_accvgpr_read_b32 v114, a18
	v_accvgpr_read_b32 v113, a17
	v_accvgpr_read_b32 v112, a16
	v_mfma_f32_32x32x16_bf16 a[16:31], v[128:131], v[128:131], 0
	v_mov_b32_e32 v128, 0
	v_add_co_u32_e64 v162, s[0:1], s0, v156
	v_accvgpr_write_b32 a204, v14
	v_mov_b32_e32 v129, v128
	v_mov_b32_e32 v130, v128
	v_mov_b32_e32 v131, v128
	v_addc_co_u32_e64 v163, s[0:1], 0, v157, s[0:1]
	s_mov_b32 s0, 0x16120000
	s_nop 0
	v_add_co_u32_e64 v164, s[0:1], s0, v156
	v_accvgpr_read_b32 v0, a112
	s_nop 0
	v_addc_co_u32_e64 v165, s[0:1], 0, v157, s[0:1]
	s_mov_b32 s0, 0x16130000
	v_accvgpr_read_b32 v1, a113
	v_accvgpr_read_b32 v2, a114
	v_accvgpr_read_b32 v3, a115
	v_accvgpr_read_b32 v4, a116
	v_accvgpr_read_b32 v5, a117
	v_accvgpr_read_b32 v6, a118
	v_accvgpr_read_b32 v7, a119
	v_accvgpr_read_b32 v8, a120
	v_accvgpr_read_b32 v9, a121
	v_accvgpr_read_b32 v10, a122
	v_accvgpr_read_b32 v11, a123
	v_accvgpr_read_b32 v12, a124
	v_accvgpr_read_b32 v13, a125
	v_accvgpr_read_b32 v14, a126
	v_accvgpr_read_b32 v15, a127
	v_mfma_f32_32x32x16_bf16 a[112:127], v[128:131], v[128:131], 0
	v_mov_b32_e32 v128, 0
	v_add_co_u32_e64 v166, s[0:1], s0, v156
	v_accvgpr_read_b32 v111, a63
	v_mov_b32_e32 v129, v128
	v_mov_b32_e32 v130, v128
	v_mov_b32_e32 v131, v128
	v_addc_co_u32_e64 v167, s[0:1], 0, v157, s[0:1]
	v_add_co_u32_e64 v168, s[0:1], s36, v156
	v_accvgpr_read_b32 v110, a62
	s_nop 0
	v_addc_co_u32_e64 v169, s[0:1], 0, v157, s[0:1]
	s_mov_b32 s0, 0x1a110000
	s_nop 0
	v_add_co_u32_e64 v170, s[0:1], s0, v156
	v_accvgpr_read_b32 v109, a61
	v_accvgpr_read_b32 v108, a60
	v_accvgpr_read_b32 v107, a59
	v_accvgpr_read_b32 v106, a58
	v_accvgpr_read_b32 v105, a57
	v_accvgpr_read_b32 v104, a56
	v_accvgpr_read_b32 v103, a55
	v_accvgpr_read_b32 v102, a54
	v_accvgpr_read_b32 v101, a53
	v_accvgpr_read_b32 v100, a52
	v_accvgpr_read_b32 v99, a51
	v_accvgpr_read_b32 v98, a50
	v_accvgpr_read_b32 v97, a49
	v_accvgpr_read_b32 v96, a48
	v_mfma_f32_32x32x16_bf16 a[48:63], v[128:131], v[128:131], 0
	global_load_dwordx4 v[128:131], v[160:161], off
	v_accvgpr_write_b32 a225, v133
	v_addc_co_u32_e64 v171, s[0:1], 0, v157, s[0:1]
	v_accvgpr_write_b32 a224, v132
	global_load_dwordx4 v[132:135], v[162:163], off
	s_mov_b32 s0, 0x1a120000
	global_load_dwordx4 v[136:139], v[164:165], off
	global_load_dwordx4 v[140:143], v[166:167], off
	v_add_co_u32_e64 v172, s[0:1], s0, v156
	global_load_dwordx4 v[144:147], v[168:169], off
	global_load_dwordx4 v[148:151], v[170:171], off
	v_addc_co_u32_e64 v173, s[0:1], 0, v157, s[0:1]
	s_mov_b32 s0, 0x1a130000
	s_nop 0
	v_add_co_u32_e64 v174, s[0:1], s0, v156
	global_load_dwordx4 v[152:155], v[172:173], off
	s_nop 0
	v_addc_co_u32_e64 v175, s[0:1], 0, v157, s[0:1]
	global_load_dwordx4 v[156:159], v[174:175], off
	s_waitcnt lgkmcnt(0)
	s_barrier
	s_waitcnt vmcnt(7)
	ds_write_b128 v196, v[128:131]
	s_waitcnt vmcnt(6)
	ds_write_b128 v196, v[132:135] offset:4608
	s_waitcnt vmcnt(5)
	ds_write_b128 v196, v[136:139] offset:9216
	s_waitcnt vmcnt(4)
	ds_write_b128 v196, v[140:143] offset:13824
	s_waitcnt vmcnt(3)
	ds_write_b128 v197, v[144:147]
	s_waitcnt vmcnt(2)
	ds_write_b128 v197, v[148:151] offset:4608
	s_waitcnt vmcnt(1)
	ds_write_b128 v197, v[152:155] offset:9216
	s_waitcnt vmcnt(0)
	ds_write_b128 v197, v[156:159] offset:13824
	s_waitcnt lgkmcnt(0)
	s_barrier
	global_load_dwordx4 v[144:147], v[160:161], off offset:128
	global_load_dwordx4 v[148:151], v[162:163], off offset:128
	global_load_dwordx4 v[152:155], v[164:165], off offset:128
	global_load_dwordx4 v[156:159], v[166:167], off offset:128
	global_load_dwordx4 v[128:131], v[168:169], off offset:128
	global_load_dwordx4 v[132:135], v[170:171], off offset:128
	global_load_dwordx4 v[136:139], v[172:173], off offset:128
	global_load_dwordx4 v[140:143], v[174:175], off offset:128
	v_add_u32_e32 v218, v192, v193
	v_accvgpr_write_b32 a195, v192
	v_accvgpr_write_b32 a198, v193
	ds_read_b128 v[176:179], v198
	ds_read_b128 v[192:195], v247
	ds_read_b128 v[180:183], v198 offset:32
	ds_read_b128 a[244:247], v247 offset:32
	ds_read_b128 a[248:251], v247 offset:4608
	s_waitcnt lgkmcnt(3)
	v_mfma_f32_32x32x16_bf16 a[64:79], v[192:195], v[176:179], a[64:79]
	ds_read_b128 a[252:255], v247 offset:9216
	s_waitcnt lgkmcnt(2)
	v_mfma_f32_32x32x16_bf16 a[64:79], a[244:247], v[180:183], a[64:79]
	ds_read_b128 v[192:195], v247 offset:13824
	s_waitcnt lgkmcnt(2)
	v_mfma_f32_32x32x16_bf16 a[80:95], a[248:251], v[176:179], a[80:95]
	ds_read_b128 a[244:247], v218
	s_waitcnt lgkmcnt(2)
	v_mfma_f32_32x32x16_bf16 a[96:111], a[252:255], v[176:179], a[96:111]
	ds_read_b128 a[248:251], v218 offset:16896
	s_waitcnt lgkmcnt(2)
	v_mfma_f32_32x32x16_bf16 a[112:127], v[192:195], v[176:179], a[112:127]
	ds_read_b128 a[252:255], v218 offset:33792
	s_waitcnt lgkmcnt(2)
	v_mfma_f32_32x32x16_bf16 a[32:47], a[244:247], v[176:179], a[32:47]
	ds_read_b128 v[192:195], v218 offset:50688
	s_waitcnt lgkmcnt(2)
	v_mfma_f32_32x32x16_bf16 a[0:15], a[248:251], v[176:179], a[0:15]
	ds_read_b128 a[244:247], v247 offset:4640
	s_waitcnt lgkmcnt(2)
	v_mfma_f32_32x32x16_bf16 a[16:31], a[252:255], v[176:179], a[16:31]
	ds_read_b128 a[248:251], v247 offset:9248
	s_waitcnt lgkmcnt(2)
	v_mfma_f32_32x32x16_bf16 a[48:63], v[192:195], v[176:179], a[48:63]
	ds_read_b128 a[252:255], v247 offset:13856
	s_waitcnt lgkmcnt(2)
	v_mfma_f32_32x32x16_bf16 a[80:95], a[244:247], v[180:183], a[80:95]
	ds_read_b128 v[192:195], v218 offset:16928
	s_waitcnt lgkmcnt(2)
	v_mfma_f32_32x32x16_bf16 a[96:111], a[248:251], v[180:183], a[96:111]
	ds_read_b128 a[244:247], v218 offset:33824
	s_waitcnt lgkmcnt(2)
	v_mfma_f32_32x32x16_bf16 a[112:127], a[252:255], v[180:183], a[112:127]
	ds_read_b128 a[248:251], v218 offset:32
	s_waitcnt lgkmcnt(2)
	v_mfma_f32_32x32x16_bf16 a[0:15], v[192:195], v[180:183], a[0:15]
	ds_read_b128 a[252:255], v218 offset:50720
	s_waitcnt lgkmcnt(2)
	v_mfma_f32_32x32x16_bf16 a[16:31], a[244:247], v[180:183], a[16:31]
	ds_read_b128 v[184:187], v198 offset:64
	ds_read_b128 v[192:195], v247 offset:64
	s_waitcnt lgkmcnt(3)
	v_mfma_f32_32x32x16_bf16 a[32:47], a[248:251], v[180:183], a[32:47]
	ds_read_b128 a[244:247], v247 offset:4672
	s_waitcnt lgkmcnt(3)
	v_mfma_f32_32x32x16_bf16 a[48:63], a[252:255], v[180:183], a[48:63]
	ds_read_b128 a[248:251], v247 offset:9280
	s_waitcnt lgkmcnt(2)
	v_mfma_f32_32x32x16_bf16 a[64:79], v[192:195], v[184:187], a[64:79]
	ds_read_b128 a[252:255], v247 offset:13888
	s_waitcnt lgkmcnt(2)
	v_mfma_f32_32x32x16_bf16 a[80:95], a[244:247], v[184:187], a[80:95]
	ds_read_b128 v[192:195], v218 offset:64
	s_waitcnt lgkmcnt(2)
	v_mfma_f32_32x32x16_bf16 a[96:111], a[248:251], v[184:187], a[96:111]
	ds_read_b128 a[244:247], v218 offset:16960
	s_waitcnt lgkmcnt(2)
	v_mfma_f32_32x32x16_bf16 a[112:127], a[252:255], v[184:187], a[112:127]
	ds_read_b128 a[248:251], v218 offset:33856
	s_waitcnt lgkmcnt(2)
	v_mfma_f32_32x32x16_bf16 a[32:47], v[192:195], v[184:187], a[32:47]
	ds_read_b128 a[252:255], v218 offset:50752
	s_waitcnt lgkmcnt(2)
	v_mfma_f32_32x32x16_bf16 a[0:15], a[244:247], v[184:187], a[0:15]
	ds_read_b128 v[188:191], v198 offset:96
	ds_read_b128 v[192:195], v247 offset:96
	s_waitcnt lgkmcnt(3)
	v_mfma_f32_32x32x16_bf16 a[16:31], a[248:251], v[184:187], a[16:31]
	ds_read_b128 a[244:247], v247 offset:4704
	s_waitcnt lgkmcnt(3)
	v_mfma_f32_32x32x16_bf16 a[48:63], a[252:255], v[184:187], a[48:63]
	ds_read_b128 a[248:251], v247 offset:9312
	s_waitcnt lgkmcnt(2)
	v_mfma_f32_32x32x16_bf16 a[64:79], v[192:195], v[188:191], a[64:79]
	ds_read_b128 a[252:255], v247 offset:13920
	s_waitcnt lgkmcnt(2)
	v_mfma_f32_32x32x16_bf16 a[80:95], a[244:247], v[188:191], a[80:95]
	ds_read_b128 v[192:195], v218 offset:96
	s_waitcnt lgkmcnt(2)
	v_mfma_f32_32x32x16_bf16 a[96:111], a[248:251], v[188:191], a[96:111]
	ds_read_b128 a[244:247], v218 offset:16992
	s_waitcnt lgkmcnt(2)
	v_mfma_f32_32x32x16_bf16 a[112:127], a[252:255], v[188:191], a[112:127]
	ds_read_b128 a[248:251], v218 offset:33888
	s_waitcnt lgkmcnt(2)
	v_mfma_f32_32x32x16_bf16 a[32:47], v[192:195], v[188:191], a[32:47]
	s_waitcnt lgkmcnt(1)
	v_mfma_f32_32x32x16_bf16 a[0:15], a[244:247], v[188:191], a[0:15]
	s_waitcnt lgkmcnt(0)
	v_mfma_f32_32x32x16_bf16 a[16:31], a[248:251], v[188:191], a[16:31]
	ds_read_b128 v[188:191], v247 offset:32
	ds_read_b128 v[192:195], v218 offset:32
	ds_read_b128 v[184:187], v218 offset:50688
	ds_read_b128 v[176:179], v198 offset:96
	ds_read_b128 v[180:183], v218 offset:50784
	s_waitcnt lgkmcnt(0)
	s_barrier
	s_waitcnt vmcnt(7)
	ds_write_b128 v196, v[144:147]
	s_waitcnt vmcnt(6)
	ds_write_b128 v196, v[148:151] offset:4608
	s_waitcnt vmcnt(5)
	ds_write_b128 v196, v[152:155] offset:9216
	s_waitcnt vmcnt(4)
	ds_write_b128 v196, v[156:159] offset:13824
	s_waitcnt vmcnt(3)
	ds_write_b128 v197, v[128:131]
	s_waitcnt vmcnt(2)
	ds_write_b128 v197, v[132:135] offset:4608
	s_waitcnt vmcnt(1)
	ds_write_b128 v197, v[136:139] offset:9216
	s_waitcnt vmcnt(0)
	ds_write_b128 v197, v[140:143] offset:13824
	s_waitcnt lgkmcnt(0)
	s_barrier
	global_load_dwordx4 v[144:147], v[160:161], off offset:256
	global_load_dwordx4 v[148:151], v[162:163], off offset:256
	global_load_dwordx4 v[152:155], v[164:165], off offset:256
	global_load_dwordx4 v[156:159], v[166:167], off offset:256
	global_load_dwordx4 v[128:131], v[168:169], off offset:256
	global_load_dwordx4 v[132:135], v[170:171], off offset:256
	global_load_dwordx4 v[136:139], v[172:173], off offset:256
	global_load_dwordx4 v[140:143], v[174:175], off offset:256
	v_mfma_f32_32x32x16_bf16 a[48:63], v[180:183], v[176:179], a[48:63]
	ds_read_b128 v[176:179], v198
	ds_read_b128 v[192:195], v247
	ds_read_b128 v[180:183], v198 offset:32
	ds_read_b128 a[244:247], v247 offset:32
	ds_read_b128 a[248:251], v247 offset:4608
	s_waitcnt lgkmcnt(3)
	v_mfma_f32_32x32x16_bf16 a[64:79], v[192:195], v[176:179], a[64:79]
	ds_read_b128 a[252:255], v247 offset:9216
	s_waitcnt lgkmcnt(2)
	v_mfma_f32_32x32x16_bf16 a[64:79], a[244:247], v[180:183], a[64:79]
	ds_read_b128 v[192:195], v247 offset:13824
	s_waitcnt lgkmcnt(2)
	v_mfma_f32_32x32x16_bf16 a[80:95], a[248:251], v[176:179], a[80:95]
	ds_read_b128 a[244:247], v218 offset:128
	s_waitcnt lgkmcnt(2)
	v_mfma_f32_32x32x16_bf16 a[96:111], a[252:255], v[176:179], a[96:111]
	ds_read_b128 a[248:251], v218 offset:17024
	s_waitcnt lgkmcnt(2)
	v_mfma_f32_32x32x16_bf16 a[112:127], v[192:195], v[176:179], a[112:127]
	ds_read_b128 a[252:255], v218 offset:33920
	s_waitcnt lgkmcnt(2)
	v_mfma_f32_32x32x16_bf16 a[32:47], a[244:247], v[176:179], a[32:47]
	ds_read_b128 v[192:195], v218 offset:50816
	s_waitcnt lgkmcnt(2)
	v_mfma_f32_32x32x16_bf16 a[0:15], a[248:251], v[176:179], a[0:15]
	ds_read_b128 a[244:247], v247 offset:4640
	s_waitcnt lgkmcnt(2)
	v_mfma_f32_32x32x16_bf16 a[16:31], a[252:255], v[176:179], a[16:31]
	ds_read_b128 a[248:251], v247 offset:9248
	s_waitcnt lgkmcnt(2)
	v_mfma_f32_32x32x16_bf16 a[48:63], v[192:195], v[176:179], a[48:63]
	ds_read_b128 a[252:255], v247 offset:13856
	s_waitcnt lgkmcnt(2)
	v_mfma_f32_32x32x16_bf16 a[80:95], a[244:247], v[180:183], a[80:95]
	ds_read_b128 v[192:195], v218 offset:17056
	s_waitcnt lgkmcnt(2)
	v_mfma_f32_32x32x16_bf16 a[96:111], a[248:251], v[180:183], a[96:111]
	ds_read_b128 a[244:247], v218 offset:33952
	s_waitcnt lgkmcnt(2)
	v_mfma_f32_32x32x16_bf16 a[112:127], a[252:255], v[180:183], a[112:127]
	ds_read_b128 a[248:251], v218 offset:160
	s_waitcnt lgkmcnt(2)
	v_mfma_f32_32x32x16_bf16 a[0:15], v[192:195], v[180:183], a[0:15]
	ds_read_b128 a[252:255], v218 offset:50848
	s_waitcnt lgkmcnt(2)
	v_mfma_f32_32x32x16_bf16 a[16:31], a[244:247], v[180:183], a[16:31]
	ds_read_b128 v[184:187], v198 offset:64
	ds_read_b128 v[192:195], v247 offset:64
	s_waitcnt lgkmcnt(3)
	v_mfma_f32_32x32x16_bf16 a[32:47], a[248:251], v[180:183], a[32:47]
	ds_read_b128 a[244:247], v247 offset:4672
	s_waitcnt lgkmcnt(3)
	v_mfma_f32_32x32x16_bf16 a[48:63], a[252:255], v[180:183], a[48:63]
	ds_read_b128 a[248:251], v247 offset:9280
	s_waitcnt lgkmcnt(2)
	v_mfma_f32_32x32x16_bf16 a[64:79], v[192:195], v[184:187], a[64:79]
	ds_read_b128 a[252:255], v247 offset:13888
	s_waitcnt lgkmcnt(2)
	v_mfma_f32_32x32x16_bf16 a[80:95], a[244:247], v[184:187], a[80:95]
	ds_read_b128 v[192:195], v218 offset:192
	s_waitcnt lgkmcnt(2)
	v_mfma_f32_32x32x16_bf16 a[96:111], a[248:251], v[184:187], a[96:111]
	ds_read_b128 a[244:247], v218 offset:17088
	s_waitcnt lgkmcnt(2)
	v_mfma_f32_32x32x16_bf16 a[112:127], a[252:255], v[184:187], a[112:127]
	ds_read_b128 a[248:251], v218 offset:33984
	s_waitcnt lgkmcnt(2)
	v_mfma_f32_32x32x16_bf16 a[32:47], v[192:195], v[184:187], a[32:47]
	ds_read_b128 a[252:255], v218 offset:50880
	s_waitcnt lgkmcnt(2)
	v_mfma_f32_32x32x16_bf16 a[0:15], a[244:247], v[184:187], a[0:15]
	ds_read_b128 v[188:191], v198 offset:96
	ds_read_b128 v[192:195], v247 offset:96
	s_waitcnt lgkmcnt(3)
	v_mfma_f32_32x32x16_bf16 a[16:31], a[248:251], v[184:187], a[16:31]
	ds_read_b128 a[244:247], v247 offset:4704
	s_waitcnt lgkmcnt(3)
	v_mfma_f32_32x32x16_bf16 a[48:63], a[252:255], v[184:187], a[48:63]
	ds_read_b128 a[248:251], v247 offset:9312
	s_waitcnt lgkmcnt(2)
	v_mfma_f32_32x32x16_bf16 a[64:79], v[192:195], v[188:191], a[64:79]
	ds_read_b128 a[252:255], v247 offset:13920
	s_waitcnt lgkmcnt(2)
	v_mfma_f32_32x32x16_bf16 a[80:95], a[244:247], v[188:191], a[80:95]
	ds_read_b128 v[192:195], v218 offset:224
	s_waitcnt lgkmcnt(2)
	v_mfma_f32_32x32x16_bf16 a[96:111], a[248:251], v[188:191], a[96:111]
	ds_read_b128 a[244:247], v218 offset:17120
	s_waitcnt lgkmcnt(2)
	v_mfma_f32_32x32x16_bf16 a[112:127], a[252:255], v[188:191], a[112:127]
	ds_read_b128 a[248:251], v218 offset:34016
	s_waitcnt lgkmcnt(2)
	v_mfma_f32_32x32x16_bf16 a[32:47], v[192:195], v[188:191], a[32:47]
	s_waitcnt lgkmcnt(1)
	v_mfma_f32_32x32x16_bf16 a[0:15], a[244:247], v[188:191], a[0:15]
	s_waitcnt lgkmcnt(0)
	v_mfma_f32_32x32x16_bf16 a[16:31], a[248:251], v[188:191], a[16:31]
	ds_read_b128 v[188:191], v247 offset:32
	ds_read_b128 v[192:195], v218 offset:160
	ds_read_b128 v[184:187], v218 offset:50816
	ds_read_b128 v[176:179], v198 offset:96
	ds_read_b128 v[180:183], v218 offset:50912
	s_waitcnt lgkmcnt(0)
	s_barrier
	s_waitcnt vmcnt(7)
	ds_write_b128 v196, v[144:147]
	s_waitcnt vmcnt(6)
	ds_write_b128 v196, v[148:151] offset:4608
	s_waitcnt vmcnt(5)
	ds_write_b128 v196, v[152:155] offset:9216
	s_waitcnt vmcnt(4)
	ds_write_b128 v196, v[156:159] offset:13824
	s_waitcnt vmcnt(3)
	ds_write_b128 v197, v[128:131]
	s_waitcnt vmcnt(2)
	ds_write_b128 v197, v[132:135] offset:4608
	s_waitcnt vmcnt(1)
	ds_write_b128 v197, v[136:139] offset:9216
	s_waitcnt vmcnt(0)
	ds_write_b128 v197, v[140:143] offset:13824
	s_waitcnt lgkmcnt(0)
	s_barrier
	global_load_dwordx4 v[148:151], v[160:161], off offset:384
	global_load_dwordx4 v[152:155], v[162:163], off offset:384
	global_load_dwordx4 v[156:159], v[164:165], off offset:384
	global_load_dwordx4 v[128:131], v[166:167], off offset:384
	global_load_dwordx4 v[132:135], v[168:169], off offset:384
	global_load_dwordx4 v[136:139], v[170:171], off offset:384
	global_load_dwordx4 v[140:143], v[172:173], off offset:384
	global_load_dwordx4 v[144:147], v[174:175], off offset:384
	v_mfma_f32_32x32x16_bf16 a[48:63], v[180:183], v[176:179], a[48:63]
	ds_read_b128 v[176:179], v198
	ds_read_b128 v[192:195], v247
	ds_read_b128 a[244:247], v247 offset:4608
	ds_read_b128 a[248:251], v247 offset:9216
	s_waitcnt lgkmcnt(2)
	v_mfma_f32_32x32x16_bf16 a[64:79], v[192:195], v[176:179], a[64:79]
	ds_read_b128 a[252:255], v247 offset:13824
	s_waitcnt lgkmcnt(2)
	v_mfma_f32_32x32x16_bf16 a[80:95], a[244:247], v[176:179], a[80:95]
	ds_read_b128 v[192:195], v218 offset:256
	s_waitcnt lgkmcnt(2)
	v_mfma_f32_32x32x16_bf16 a[96:111], a[248:251], v[176:179], a[96:111]
	ds_read_b128 a[244:247], v218 offset:17152
	s_waitcnt lgkmcnt(2)
	v_mfma_f32_32x32x16_bf16 a[112:127], a[252:255], v[176:179], a[112:127]
	ds_read_b128 a[248:251], v218 offset:34048
	s_waitcnt lgkmcnt(2)
	v_mfma_f32_32x32x16_bf16 a[32:47], v[192:195], v[176:179], a[32:47]
	ds_read_b128 a[252:255], v218 offset:50944
	s_waitcnt lgkmcnt(2)
	v_mfma_f32_32x32x16_bf16 a[0:15], a[244:247], v[176:179], a[0:15]
	ds_read_b128 v[180:183], v198 offset:32
	ds_read_b128 v[192:195], v247 offset:32
	s_waitcnt lgkmcnt(3)
	v_mfma_f32_32x32x16_bf16 a[16:31], a[248:251], v[176:179], a[16:31]
	ds_read_b128 a[244:247], v247 offset:4640
	s_waitcnt lgkmcnt(3)
	v_mfma_f32_32x32x16_bf16 a[48:63], a[252:255], v[176:179], a[48:63]
	ds_read_b128 a[248:251], v247 offset:9248
	s_waitcnt lgkmcnt(2)
	v_mfma_f32_32x32x16_bf16 a[64:79], v[192:195], v[180:183], a[64:79]
	ds_read_b128 a[252:255], v247 offset:13856
	s_waitcnt lgkmcnt(2)
	v_mfma_f32_32x32x16_bf16 a[80:95], a[244:247], v[180:183], a[80:95]
	ds_read_b128 v[192:195], v218 offset:288
	s_waitcnt lgkmcnt(2)
	v_mfma_f32_32x32x16_bf16 a[96:111], a[248:251], v[180:183], a[96:111]
	ds_read_b128 a[244:247], v218 offset:17184
	s_waitcnt lgkmcnt(2)
	v_mfma_f32_32x32x16_bf16 a[112:127], a[252:255], v[180:183], a[112:127]
	ds_read_b128 a[248:251], v218 offset:34080
	s_waitcnt lgkmcnt(2)
	v_mfma_f32_32x32x16_bf16 a[32:47], v[192:195], v[180:183], a[32:47]
	ds_read_b128 a[252:255], v218 offset:50976
	s_waitcnt lgkmcnt(2)
	v_mfma_f32_32x32x16_bf16 a[0:15], a[244:247], v[180:183], a[0:15]
	ds_read_b128 v[184:187], v198 offset:64
	ds_read_b128 v[192:195], v247 offset:64
	s_waitcnt lgkmcnt(3)
	v_mfma_f32_32x32x16_bf16 a[16:31], a[248:251], v[180:183], a[16:31]
	ds_read_b128 a[244:247], v247 offset:4672
	s_waitcnt lgkmcnt(3)
	v_mfma_f32_32x32x16_bf16 a[48:63], a[252:255], v[180:183], a[48:63]
	ds_read_b128 a[248:251], v247 offset:9280
	s_waitcnt lgkmcnt(2)
	v_mfma_f32_32x32x16_bf16 a[64:79], v[192:195], v[184:187], a[64:79]
	ds_read_b128 a[252:255], v247 offset:13888
	s_waitcnt lgkmcnt(2)
	v_mfma_f32_32x32x16_bf16 a[80:95], a[244:247], v[184:187], a[80:95]
	ds_read_b128 v[192:195], v218 offset:320
	s_waitcnt lgkmcnt(2)
	v_mfma_f32_32x32x16_bf16 a[96:111], a[248:251], v[184:187], a[96:111]
	ds_read_b128 a[244:247], v218 offset:17216
	s_waitcnt lgkmcnt(2)
	v_mfma_f32_32x32x16_bf16 a[112:127], a[252:255], v[184:187], a[112:127]
	ds_read_b128 a[248:251], v218 offset:34112
	s_waitcnt lgkmcnt(2)
	v_mfma_f32_32x32x16_bf16 a[32:47], v[192:195], v[184:187], a[32:47]
	ds_read_b128 a[252:255], v218 offset:51008
	s_waitcnt lgkmcnt(2)
	v_mfma_f32_32x32x16_bf16 a[0:15], a[244:247], v[184:187], a[0:15]
	ds_read_b128 v[188:191], v198 offset:96
	ds_read_b128 v[192:195], v247 offset:96
	s_waitcnt lgkmcnt(3)
	v_mfma_f32_32x32x16_bf16 a[16:31], a[248:251], v[184:187], a[16:31]
	ds_read_b128 a[244:247], v247 offset:4704
	s_waitcnt lgkmcnt(3)
	v_mfma_f32_32x32x16_bf16 a[48:63], a[252:255], v[184:187], a[48:63]
	ds_read_b128 a[248:251], v247 offset:9312
	s_waitcnt lgkmcnt(2)
	v_mfma_f32_32x32x16_bf16 a[64:79], v[192:195], v[188:191], a[64:79]
	ds_read_b128 a[252:255], v247 offset:13920
	s_waitcnt lgkmcnt(2)
	v_mfma_f32_32x32x16_bf16 a[80:95], a[244:247], v[188:191], a[80:95]
	ds_read_b128 v[192:195], v218 offset:352
	s_waitcnt lgkmcnt(2)
	v_mfma_f32_32x32x16_bf16 a[96:111], a[248:251], v[188:191], a[96:111]
	ds_read_b128 a[244:247], v218 offset:17248
	s_waitcnt lgkmcnt(2)
	v_mfma_f32_32x32x16_bf16 a[112:127], a[252:255], v[188:191], a[112:127]
	s_waitcnt lgkmcnt(1)
	v_mfma_f32_32x32x16_bf16 a[32:47], v[192:195], v[188:191], a[32:47]
	s_waitcnt lgkmcnt(0)
	v_mfma_f32_32x32x16_bf16 a[0:15], a[244:247], v[188:191], a[0:15]
	ds_read_b128 v[164:167], v198 offset:96
	ds_read_b128 v[168:171], v218 offset:34144
	ds_read_b128 v[160:163], v218 offset:51040
	s_waitcnt lgkmcnt(0)
	s_barrier
	s_waitcnt vmcnt(7)
	ds_write_b128 v196, v[148:151]
	s_waitcnt vmcnt(6)
	ds_write_b128 v196, v[152:155] offset:4608
	s_waitcnt vmcnt(5)
	ds_write_b128 v196, v[156:159] offset:9216
	s_waitcnt vmcnt(4)
	ds_write_b128 v196, v[128:131] offset:13824
	s_waitcnt vmcnt(3)
	ds_write_b128 v197, v[132:135]
	s_waitcnt vmcnt(2)
	ds_write_b128 v197, v[136:139] offset:4608
	s_waitcnt vmcnt(1)
	ds_write_b128 v197, v[140:143] offset:9216
	s_waitcnt vmcnt(0)
	ds_write_b128 v197, v[144:147] offset:13824
	s_waitcnt lgkmcnt(0)
	v_mfma_f32_32x32x16_bf16 a[16:31], v[168:171], v[164:167], a[16:31]
	s_barrier
	v_mfma_f32_32x32x16_bf16 a[48:63], v[160:163], v[164:167], a[48:63]
	ds_read_b128 v[128:131], v247
	ds_read_b128 v[164:167], v198
	ds_read_b128 v[136:139], v198 offset:32
	ds_read_b128 v[132:135], v247 offset:32
	v_mov_b32_e32 v231, v230
	v_pk_mul_f32 v[210:211], v[230:231], v[90:91]
	s_waitcnt lgkmcnt(2)
	v_mfma_f32_32x32x16_bf16 a[64:79], v[128:131], v[164:167], a[64:79]
	ds_read_b128 v[128:131], v247 offset:4608
	ds_read_b128 v[140:143], v247 offset:4640
	v_accvgpr_read_b32 v90, a222
	v_mul_f32_e64 v214, v230, v94
	v_mul_f32_e64 v215, v231, v95
	v_accvgpr_read_b32 v91, a223
	v_accvgpr_write_b32 a196, v196
	v_accvgpr_write_b32 a197, v197
	v_accvgpr_write_b32 a201, v198
	s_waitcnt lgkmcnt(1)
	v_mfma_f32_32x32x16_bf16 a[80:95], v[128:131], v[164:167], a[80:95]
	ds_read_b128 v[128:131], v247 offset:9216
	ds_read_b128 v[144:147], v247 offset:9248
	v_mul_f32_e64 v212, v230, v92
	v_mul_f32_e64 v213, v231, v93
	v_mul_f32_e64 v208, v230, v88
	v_mul_f32_e64 v209, v231, v89
	v_pk_mul_f32 v[206:207], v[230:231], v[86:87]
	v_pk_mul_f32 v[204:205], v[230:231], v[84:85]
	s_mov_b32 s0, 0
	v_accvgpr_write_b32 a193, v253
	s_waitcnt lgkmcnt(1)
	v_mfma_f32_32x32x16_bf16 a[96:111], v[128:131], v[164:167], a[96:111]
	ds_read_b128 v[128:131], v247 offset:13824
	ds_read_b128 v[148:151], v247 offset:13856
	v_mul_f32_e64 v126, v230, v126
	v_mul_f32_e64 v127, v231, v127
	v_mul_f32_e64 v124, v230, v124
	v_mul_f32_e64 v125, v231, v125
	v_pk_mul_f32 v[122:123], v[230:231], v[122:123]
	v_pk_mul_f32 v[120:121], v[230:231], v[120:121]
	v_pk_mul_f32 v[118:119], v[230:231], v[118:119]
	v_pk_mul_f32 v[116:117], v[230:231], v[116:117]
	s_waitcnt lgkmcnt(1)
	v_mfma_f32_32x32x16_bf16 a[112:127], v[128:131], v[164:167], a[112:127]
	ds_read_b128 v[128:131], v218 offset:384
	ds_read_b128 v[160:163], v218 offset:416
	v_mul_f32_e64 v114, v230, v114
	v_mul_f32_e64 v115, v231, v115
	v_mul_f32_e64 v110, v230, v110
	v_mul_f32_e64 v111, v231, v111
	v_pk_mul_f32 v[108:109], v[230:231], v[108:109]
	v_pk_mul_f32 v[106:107], v[230:231], v[106:107]
	v_pk_mul_f32 v[104:105], v[230:231], v[104:105]
	v_pk_mul_f32 v[102:103], v[230:231], v[102:103]
	s_waitcnt lgkmcnt(1)
	v_mfma_f32_32x32x16_bf16 a[32:47], v[128:131], v[164:167], a[32:47]
	ds_read_b128 v[128:131], v218 offset:17280
	ds_read_b128 v[156:159], v218 offset:17312
	v_mul_f32_e64 v100, v230, v100
	v_mul_f32_e64 v101, v231, v101
	v_mul_f32_e64 v98, v230, v98
	v_mul_f32_e64 v99, v231, v99
	v_pk_mul_f32 v[112:113], v[90:91], v[112:113]
	v_pk_mul_f32 v[96:97], v[90:91], v[96:97]
	v_accvgpr_read_b32 v94, a214
	v_accvgpr_read_b32 v95, a215
	v_mfma_f32_32x32x16_bf16 a[64:79], v[132:135], v[136:139], a[64:79]
	s_waitcnt lgkmcnt(1)
	v_mfma_f32_32x32x16_bf16 a[0:15], v[128:131], v[164:167], a[0:15]
	ds_read_b128 v[128:131], v218 offset:34176
	ds_read_b128 v[152:155], v218 offset:34208
	v_mfma_f32_32x32x16_bf16 a[80:95], v[140:143], v[136:139], a[80:95]
	v_mfma_f32_32x32x16_bf16 a[96:111], v[144:147], v[136:139], a[96:111]
	s_waitcnt lgkmcnt(1)
	v_mfma_f32_32x32x16_bf16 a[16:31], v[128:131], v[164:167], a[16:31]
	ds_read_b128 v[168:171], v218 offset:51072
	ds_read_b128 v[144:147], v218 offset:51104
	ds_read_b128 v[132:135], v198 offset:64
	ds_read_b128 v[128:131], v198 offset:96
	ds_read_b128 v[200:203], v247 offset:64
	ds_read_b128 v[188:191], v247 offset:96
	ds_read_b128 v[192:195], v247 offset:4672
	ds_read_b128 v[184:187], v247 offset:4704
	s_waitcnt lgkmcnt(3)
	v_mfma_f32_32x32x16_bf16 a[64:79], v[200:203], v[132:135], a[64:79]
	v_mul_f32_e64 v202, v230, v82
	v_mul_f32_e64 v203, v231, v83
	v_mul_f32_e64 v200, v90, v80
	v_mul_f32_e64 v201, v91, v81
	v_accvgpr_write_b32 a241, v215
	v_accvgpr_write_b32 a240, v214
	v_accvgpr_write_b32 a239, v213
	v_accvgpr_write_b32 a238, v212
	v_mfma_f32_32x32x16_bf16 a[112:127], v[148:151], v[136:139], a[112:127]
	ds_read_b128 v[196:199], v247 offset:9280
	ds_read_b128 v[180:183], v247 offset:9312
	ds_read_b128 v[176:179], v247 offset:13888
	ds_read_b128 v[172:175], v247 offset:13920
	ds_read_b128 v[148:151], v218 offset:448
	ds_read_b128 v[140:143], v218 offset:480
	v_accvgpr_write_b32 a237, v211
	v_accvgpr_write_b32 a236, v210
	v_accvgpr_write_b32 a235, v209
	v_accvgpr_write_b32 a234, v208
	v_accvgpr_write_b32 a233, v207
	v_accvgpr_write_b32 a232, v206
	v_accvgpr_write_b32 a231, v205
	v_accvgpr_write_b32 a230, v204
	v_accvgpr_write_b32 a229, v203
	v_accvgpr_write_b32 a228, v202
	v_accvgpr_write_b32 a227, v201
	v_accvgpr_write_b32 a226, v200
	s_waitcnt lgkmcnt(7)
	v_mfma_f32_32x32x16_bf16 a[80:95], v[192:195], v[132:135], a[80:95]
	ds_read_b128 v[212:215], v218 offset:17344
	ds_read_b128 v[204:207], v218 offset:17376
	ds_read_b128 v[208:211], v218 offset:34240
	ds_read_b128 v[200:203], v218 offset:34272
	s_waitcnt lgkmcnt(9)
	v_mfma_f32_32x32x16_bf16 a[96:111], v[196:199], v[132:135], a[96:111]
	ds_read_b128 v[196:199], v218 offset:51136
	ds_read_b128 v[192:195], v218 offset:51168
	s_nop 0
	v_mbcnt_lo_u32_b32 v80, -1, s0
	v_mbcnt_hi_u32_b32 v248, -1, v80
	v_bfe_u32 v246, v248, 5, 1
	v_mad_i32_i24 v84, v246, -4, -1
	v_mad_i32_i24 v80, v246, -4, v217
	v_cvt_f32_u32_e32 v81, v80
	v_add_u32_e32 v82, v84, v217
	v_cvt_f32_u32_e32 v83, v82
	v_mfma_f32_32x32x16_bf16 a[64:79], v[188:191], v[128:131], a[64:79]
	v_mul_f32_e32 v81, v216, v81
	v_exp_f32_e32 v81, v81
	v_mul_f32_e32 v83, v216, v83
	v_exp_f32_e32 v83, v83
	v_cmp_lt_i32_e64 s[0:1], -1, v80
	v_subrev_u32_e32 v190, 32, v217
	v_or_b32_e32 v249, s17, v248
	v_cndmask_b32_e64 v80, 0, v81, s[0:1]
	v_cmp_lt_i32_e64 s[0:1], -1, v82
	v_mfma_f32_32x32x16_bf16 a[80:95], v[184:187], v[128:131], a[80:95]
	v_subrev_u32_e32 v186, 64, v217
	v_cndmask_b32_e64 v81, 0, v83, s[0:1]
	v_accvgpr_read_b32 v83, a65
	v_accvgpr_read_b32 v82, a64
	v_mul_f32_e64 v188, v82, v80
	v_mul_f32_e64 v189, v83, v81
	v_mad_i32_i24 v80, v246, -4, v190
	v_cvt_f32_u32_e32 v81, v80
	v_add_u32_e32 v82, v84, v190
	v_cvt_f32_u32_e32 v83, v82
	v_cmp_lt_i32_e64 s[0:1], -1, v80
	v_mul_f32_e32 v81, v216, v81
	v_exp_f32_e32 v81, v81
	v_mul_f32_e32 v83, v216, v83
	v_exp_f32_e32 v83, v83
	s_waitcnt lgkmcnt(9)
	v_mfma_f32_32x32x16_bf16 a[112:127], v[176:179], v[132:135], a[112:127]
	v_cndmask_b32_e64 v80, 0, v81, s[0:1]
	v_cmp_lt_i32_e64 s[0:1], -1, v82
	v_lshrrev_b32_e32 v252, 3, v249
	v_lshlrev_b64 v[88:89], 12, v[252:253]
	v_cndmask_b32_e64 v81, 0, v83, s[0:1]
	v_accvgpr_read_b32 v83, a81
	v_accvgpr_read_b32 v82, a80
	v_pk_mul_f32 v[184:185], v[82:83], v[80:81]
	v_mad_i32_i24 v80, v246, -4, v186
	v_cvt_f32_u32_e32 v81, v80
	v_add_u32_e32 v82, v84, v186
	v_cvt_f32_u32_e32 v83, v82
	v_mfma_f32_32x32x16_bf16 a[96:111], v[180:183], v[128:131], a[96:111]
	v_mul_f32_e32 v81, v216, v81
	v_exp_f32_e32 v81, v81
	v_mul_f32_e32 v83, v216, v83
	v_add_u32_e32 v180, 0xffffffa0, v217
	v_exp_f32_e32 v83, v83
	v_mad_i32_i24 v85, v246, -4, v180
	v_cmp_lt_i32_e64 s[0:1], -1, v80
	v_cvt_f32_u32_e32 v86, v85
	v_add_u32_e32 v84, v84, v180
	v_cndmask_b32_e64 v80, 0, v81, s[0:1]
	v_cmp_lt_i32_e64 s[0:1], -1, v82
	v_cvt_f32_u32_e32 v87, v84
	s_waitcnt lgkmcnt(8)
	v_mfma_f32_32x32x16_bf16 a[112:127], v[172:175], v[128:131], a[112:127]
	v_cndmask_b32_e64 v81, 0, v83, s[0:1]
	v_accvgpr_read_b32 v82, a96
	v_accvgpr_read_b32 v83, a97
	v_mul_f32_e64 v176, v82, v80
	v_mul_f32_e64 v177, v83, v81
	v_mul_f32_e32 v80, v216, v86
	v_exp_f32_e32 v80, v80
	v_mul_f32_e32 v81, v216, v87
	v_exp_f32_e32 v81, v81
	v_cmp_lt_i32_e64 s[0:1], -1, v85
	v_mfma_f32_32x32x16_bf16 a[48:63], v[168:171], v[164:167], a[48:63]
	v_accvgpr_read_b32 v178, a218
	v_cndmask_b32_e64 v80, 0, v80, s[0:1]
	v_cmp_lt_i32_e64 s[0:1], -1, v84
	v_accvgpr_read_b32 v82, a112
	v_accvgpr_read_b32 v83, a113
	v_cndmask_b32_e64 v81, 0, v81, s[0:1]
	v_pk_mul_f32 v[172:173], v[82:83], v[80:81]
	v_pk_mul_f32 v[80:81], v[230:231], v[78:79]
	v_pk_mul_f32 v[78:79], v[230:231], v[76:77]
	v_pk_mul_f32 v[76:77], v[230:231], v[74:75]
	v_pk_mul_f32 v[74:75], v[230:231], v[72:73]
	v_pk_mul_f32 v[72:73], v[230:231], v[70:71]
	v_pk_mul_f32 v[70:71], v[230:231], v[68:69]
	v_pk_mul_f32 v[68:69], v[230:231], v[66:67]
	v_pk_mul_f32 v[66:67], v[90:91], v[64:65]
	v_pk_mul_f32 v[64:65], v[230:231], v[62:63]
	v_pk_mul_f32 v[62:63], v[230:231], v[60:61]
	v_pk_mul_f32 v[60:61], v[230:231], v[58:59]
	v_pk_mul_f32 v[58:59], v[230:231], v[56:57]
	v_pk_mul_f32 v[56:57], v[230:231], v[54:55]
	v_pk_mul_f32 v[54:55], v[230:231], v[52:53]
	v_pk_mul_f32 v[52:53], v[230:231], v[50:51]
	v_pk_mul_f32 v[50:51], v[90:91], v[48:49]
	v_pk_mul_f32 v[48:49], v[230:231], v[46:47]
	v_pk_mul_f32 v[46:47], v[230:231], v[44:45]
	v_pk_mul_f32 v[44:45], v[230:231], v[42:43]
	v_pk_mul_f32 v[42:43], v[230:231], v[40:41]
	v_pk_mul_f32 v[40:41], v[230:231], v[38:39]
	v_pk_mul_f32 v[38:39], v[230:231], v[36:37]
	v_pk_mul_f32 v[36:37], v[230:231], v[34:35]
	v_pk_mul_f32 v[34:35], v[90:91], v[32:33]
	v_pk_mul_f32 v[32:33], v[230:231], v[30:31]
	v_pk_mul_f32 v[30:31], v[230:231], v[28:29]
	v_pk_mul_f32 v[28:29], v[230:231], v[26:27]
	v_pk_mul_f32 v[26:27], v[230:231], v[24:25]
	v_pk_mul_f32 v[24:25], v[230:231], v[22:23]
	v_pk_mul_f32 v[22:23], v[230:231], v[20:21]
	v_pk_mul_f32 v[20:21], v[230:231], v[18:19]
	v_pk_mul_f32 v[18:19], v[90:91], v[16:17]
	v_pk_mul_f32 v[16:17], v[230:231], v[14:15]
	v_and_b32_e32 v14, 7, v248
	s_add_u32 s0, s4, s96
	v_lshl_or_b32 v88, v14, 4, v88
	s_addc_u32 s1, s5, s97
	v_lshl_add_u64 v[92:93], s[0:1], 0, v[88:89]
	s_mov_b32 s0, 0x22100000
	v_add_co_u32_e64 v250, s[0:1], s0, v92
	v_pk_mul_f32 v[14:15], v[230:231], v[12:13]
	s_nop 0
	v_addc_co_u32_e64 v251, s[0:1], 0, v93, s[0:1]
	global_load_dwordx4 v[84:87], v[250:251], off
	s_add_u32 s0, s19, s96
	s_addc_u32 s1, s20, s97
	v_pk_mul_f32 v[12:13], v[230:231], v[10:11]
	v_pk_mul_f32 v[10:11], v[230:231], v[8:9]
	v_pk_mul_f32 v[8:9], v[230:231], v[6:7]
	v_pk_mul_f32 v[6:7], v[230:231], v[4:5]
	v_pk_mul_f32 v[4:5], v[230:231], v[2:3]
	v_pk_mul_f32 v[2:3], v[90:91], v[0:1]
	v_lshl_add_u64 v[0:1], s[0:1], 0, v[88:89]
	v_lshlrev_b32_e32 v88, 4, v248
	v_and_b32_e32 v88, 0x70, v88
	v_mad_u64_u32 v[174:175], s[0:1], v252, s27, v[88:89]
	s_mov_b32 s0, 0x22120000
	s_nop 0
	v_add_co_u32_e64 v252, s[0:1], s0, v92
	v_mfma_f32_32x32x16_bf16 a[32:47], v[160:163], v[136:139], a[32:47]
	s_nop 0
	v_addc_co_u32_e64 v253, s[0:1], 0, v93, s[0:1]
	s_mov_b32 s0, 0x22140000
	s_nop 0
	v_add_co_u32_e64 v226, s[0:1], s0, v92
	v_mad_i32_i24 v83, v246, -4, -3
	s_nop 0
	v_addc_co_u32_e64 v227, s[0:1], 0, v93, s[0:1]
	s_mov_b32 s0, 0x22160000
	s_nop 0
	v_add_co_u32_e64 v224, s[0:1], s0, v92
	v_mfma_f32_32x32x16_bf16 a[0:15], v[156:159], v[136:139], a[0:15]
	s_nop 0
	v_addc_co_u32_e64 v225, s[0:1], 0, v93, s[0:1]
	s_mov_b32 s0, 0x1e100000
	s_nop 0
	v_add_co_u32_e64 v232, s[0:1], s0, v0
	v_mad_i32_i24 v82, v246, -4, -2
	s_nop 0
	v_addc_co_u32_e64 v233, s[0:1], 0, v1, s[0:1]
	s_mov_b32 s0, 0x1e120000
	s_nop 0
	v_add_co_u32_e64 v234, s[0:1], s0, v0
	v_mfma_f32_32x32x16_bf16 a[16:31], v[152:155], v[136:139], a[16:31]
	s_nop 0
	v_addc_co_u32_e64 v235, s[0:1], 0, v1, s[0:1]
	s_mov_b32 s0, 0x1e140000
	s_nop 0
	v_add_co_u32_e64 v236, s[0:1], s0, v0
	v_add_u32_e32 v231, 0x10800, v174
	s_nop 0
	v_addc_co_u32_e64 v237, s[0:1], 0, v1, s[0:1]
	v_mfma_f32_32x32x16_bf16 a[48:63], v[144:147], v[136:139], a[48:63]
	s_mov_b32 s0, 0x1e160000
	v_add_co_u32_e64 v238, s[0:1], s0, v0
	global_load_dwordx4 v[88:91], v[252:253], off
	s_nop 0
	v_addc_co_u32_e64 v239, s[0:1], 0, v1, s[0:1]
	s_mov_b32 s0, 0x1e180000
	s_nop 0
	v_add_co_u32_e64 v240, s[0:1], s0, v0
	s_waitcnt lgkmcnt(7)
	v_mfma_f32_32x32x16_bf16 a[32:47], v[148:151], v[132:135], a[32:47]
	v_addc_co_u32_e64 v241, s[0:1], 0, v1, s[0:1]
	s_mov_b32 s0, 0x1e1a0000
	s_nop 0
	v_add_co_u32_e64 v242, s[0:1], s0, v0
	global_load_dwordx4 v[164:167], v[226:227], off
	global_load_dwordx4 v[160:163], v[224:225], off
	v_addc_co_u32_e64 v243, s[0:1], 0, v1, s[0:1]
	s_waitcnt lgkmcnt(5)
	v_mfma_f32_32x32x16_bf16 a[0:15], v[212:215], v[132:135], a[0:15]
	s_mov_b32 s0, 0x1e1c0000
	v_add_co_u32_e64 v244, s[0:1], s0, v0
	v_accvgpr_read_b32 v92, a212
	s_nop 0
	v_addc_co_u32_e64 v245, s[0:1], 0, v1, s[0:1]
	s_mov_b32 s0, 0x1e1e0000
	s_waitcnt lgkmcnt(3)
	v_mfma_f32_32x32x16_bf16 a[16:31], v[208:211], v[132:135], a[16:31]
	v_add_co_u32_e64 v228, s[0:1], s0, v0
	v_add_u32_e32 v0, v83, v217
	s_nop 0
	v_addc_co_u32_e64 v229, s[0:1], 0, v1, s[0:1]
	v_cvt_f32_u32_e32 v1, v0
	v_cmp_lt_i32_e64 s[0:1], -1, v0
	s_waitcnt lgkmcnt(1)
	v_mfma_f32_32x32x16_bf16 a[48:63], v[196:199], v[132:135], a[48:63]
	v_accvgpr_read_b32 v93, a213
	v_mul_f32_e32 v1, v216, v1
	v_exp_f32_e32 v1, v1
	v_accvgpr_read_b32 v179, a219
	v_cvt_pk_bf16_f32 v196, v184, v185
	v_cndmask_b32_e64 v1, 0, v1, s[0:1]
	v_mfma_f32_32x32x16_bf16 a[32:47], v[140:143], v[128:131], a[32:47]
	global_load_dwordx4 v[156:159], v[232:233], off
	global_load_dwordx4 v[140:143], v[234:235], off
	global_load_dwordx4 v[136:139], v[236:237], off
	global_load_dwordx4 v[132:135], v[238:239], off
	v_mfma_f32_32x32x16_bf16 a[0:15], v[204:207], v[128:131], a[0:15]
	v_mfma_f32_32x32x16_bf16 a[16:31], v[200:203], v[128:131], a[16:31]
	v_cvt_pk_bf16_f32 v200, v188, v189
	s_waitcnt lgkmcnt(0)
	v_mfma_f32_32x32x16_bf16 a[48:63], v[192:195], v[128:131], a[48:63]
	global_load_dwordx4 v[128:131], v[240:241], off
	global_load_dwordx4 v[148:151], v[242:243], off
	global_load_dwordx4 v[152:155], v[244:245], off
	global_load_dwordx4 v[144:147], v[228:229], off
	s_barrier
	s_waitcnt vmcnt(11)
	ds_write_b128 v231, v[84:87]
	v_add_u32_e32 v84, v82, v217
	v_cvt_f32_u32_e32 v85, v84
	v_cmp_lt_i32_e64 s[0:1], -1, v84
	v_accvgpr_read_b32 v84, a66
	v_cvt_pk_bf16_f32 v192, v176, v177
	v_mul_f32_e32 v85, v216, v85
	v_exp_f32_e32 v85, v85
	v_accvgpr_read_b32 v176, a216
	v_accvgpr_read_b32 v177, a217
	v_cndmask_b32_e64 v0, 0, v85, s[0:1]
	v_accvgpr_read_b32 v85, a67
	v_pk_mul_f32 v[0:1], v[84:85], v[0:1]
	v_accvgpr_read_b32 v85, a83
	v_cvt_pk_bf16_f32 v201, v0, v1
	v_add_u32_e32 v0, v82, v190
	v_cvt_f32_u32_e32 v1, v0
	v_cmp_lt_i32_e64 s[0:1], -1, v0
	v_add_u32_e32 v0, v83, v190
	v_cmp_lt_i32_e64 s[6:7], -1, v0
	v_mul_f32_e32 v1, v216, v1
	v_exp_f32_e32 v84, v1
	v_cvt_f32_u32_e32 v1, v0
	s_waitcnt vmcnt(9)
	ds_write_b128 v231, v[164:167] offset:9216
	ds_write_b128 v231, v[88:91] offset:4608
	v_cndmask_b32_e64 v0, 0, v84, s[0:1]
	v_mul_f32_e32 v1, v216, v1
	v_exp_f32_e32 v1, v1
	v_accvgpr_read_b32 v84, a82
	v_mad_i32_i24 v88, v246, -4, -16
	s_waitcnt vmcnt(8)
	ds_write_b128 v231, v[160:163] offset:13824
	v_cndmask_b32_e64 v1, 0, v1, s[6:7]
	v_pk_mul_f32 v[0:1], v[84:85], v[0:1]
	v_add_u32_e32 v84, v82, v186
	v_cvt_pk_bf16_f32 v197, v0, v1
	v_add_u32_e32 v0, v83, v186
	v_cvt_f32_u32_e32 v1, v0
	v_cvt_f32_u32_e32 v85, v84
	v_cmp_lt_i32_e64 s[0:1], -1, v0
	v_add_u32_e32 v82, v82, v180
	v_mul_f32_e32 v1, v216, v1
	v_exp_f32_e32 v1, v1
	v_mul_f32_e32 v85, v216, v85
	v_exp_f32_e32 v85, v85
	v_add_u32_e32 v86, v88, v190
	v_cndmask_b32_e64 v1, 0, v1, s[0:1]
	v_cmp_lt_i32_e64 s[0:1], -1, v84
	v_accvgpr_read_b32 v84, a98
	s_nop 0
	v_cndmask_b32_e64 v0, 0, v85, s[0:1]
	v_accvgpr_read_b32 v85, a99
	v_pk_mul_f32 v[0:1], v[84:85], v[0:1]
	v_mad_i32_i24 v84, v246, -4, -8
	v_cvt_pk_bf16_f32 v193, v0, v1
	v_add_u32_e32 v0, v83, v180
	v_cvt_f32_u32_e32 v1, v0
	v_cvt_f32_u32_e32 v83, v82
	v_cmp_lt_i32_e64 s[0:1], -1, v0
	v_mad_i32_i24 v85, v246, -4, -9
	v_mul_f32_e32 v1, v216, v1
	v_exp_f32_e32 v1, v1
	v_mul_f32_e32 v83, v216, v83
	v_exp_f32_e32 v83, v83
	v_cndmask_b32_e64 v1, 0, v1, s[0:1]
	v_cmp_lt_i32_e64 s[0:1], -1, v82
	v_accvgpr_read_b32 v82, a114
	s_nop 0
	v_cndmask_b32_e64 v0, 0, v83, s[0:1]
	v_accvgpr_read_b32 v83, a115
	v_pk_mul_f32 v[168:169], v[82:83], v[0:1]
	v_add_u32_e32 v0, v84, v217
	v_cvt_f32_u32_e32 v1, v0
	v_cmp_lt_i32_e64 s[0:1], -1, v0
	v_add_u32_e32 v0, v85, v217
	v_cmp_lt_i32_e64 s[6:7], -1, v0
	v_mul_f32_e32 v1, v216, v1
	v_exp_f32_e32 v82, v1
	v_cvt_f32_u32_e32 v1, v0
	v_accvgpr_read_b32 v83, a69
	v_cndmask_b32_e64 v0, 0, v82, s[0:1]
	v_mul_f32_e32 v1, v216, v1
	v_exp_f32_e32 v1, v1
	v_accvgpr_read_b32 v82, a68
	v_cndmask_b32_e64 v1, 0, v1, s[6:7]
	v_pk_mul_f32 v[0:1], v[82:83], v[0:1]
	v_accvgpr_read_b32 v83, a85
	v_cvt_pk_bf16_f32 v202, v0, v1
	v_add_u32_e32 v0, v84, v190
	v_cvt_f32_u32_e32 v1, v0
	v_cmp_lt_i32_e64 s[0:1], -1, v0
	v_add_u32_e32 v0, v85, v190
	v_cmp_lt_i32_e64 s[6:7], -1, v0
	v_mul_f32_e32 v1, v216, v1
	v_exp_f32_e32 v82, v1
	v_cvt_f32_u32_e32 v1, v0
	v_cndmask_b32_e64 v0, 0, v82, s[0:1]
	v_mul_f32_e32 v1, v216, v1
	v_exp_f32_e32 v1, v1
	v_accvgpr_read_b32 v82, a84
	v_cndmask_b32_e64 v1, 0, v1, s[6:7]
	v_pk_mul_f32 v[0:1], v[82:83], v[0:1]
	v_accvgpr_read_b32 v83, a101
	v_cvt_pk_bf16_f32 v198, v0, v1
	v_add_u32_e32 v0, v84, v186
	v_cvt_f32_u32_e32 v1, v0
	v_cmp_lt_i32_e64 s[0:1], -1, v0
	v_add_u32_e32 v0, v85, v186
	v_cmp_lt_i32_e64 s[6:7], -1, v0
	v_mul_f32_e32 v1, v216, v1
	v_exp_f32_e32 v82, v1
	v_cvt_f32_u32_e32 v1, v0
	v_cndmask_b32_e64 v0, 0, v82, s[0:1]
	v_mul_f32_e32 v1, v216, v1
	v_exp_f32_e32 v1, v1
	v_accvgpr_read_b32 v82, a100
	v_cndmask_b32_e64 v1, 0, v1, s[6:7]
	v_pk_mul_f32 v[0:1], v[82:83], v[0:1]
	v_accvgpr_read_b32 v83, a117
	v_cvt_pk_bf16_f32 v194, v0, v1
	v_add_u32_e32 v0, v84, v180
	v_cvt_f32_u32_e32 v1, v0
	v_cmp_lt_i32_e64 s[0:1], -1, v0
	v_add_u32_e32 v0, v85, v180
	v_cmp_lt_i32_e64 s[6:7], -1, v0
	v_mul_f32_e32 v1, v216, v1
	v_exp_f32_e32 v82, v1
	v_cvt_f32_u32_e32 v1, v0
	v_mad_i32_i24 v84, v246, -4, -10
	v_mad_i32_i24 v85, v246, -4, -11
	v_cndmask_b32_e64 v0, 0, v82, s[0:1]
	v_mul_f32_e32 v1, v216, v1
	v_exp_f32_e32 v1, v1
	v_accvgpr_read_b32 v82, a116
	v_cndmask_b32_e64 v1, 0, v1, s[6:7]
	v_pk_mul_f32 v[170:171], v[82:83], v[0:1]
	v_add_u32_e32 v0, v84, v217
	v_cvt_f32_u32_e32 v1, v0
	v_cmp_lt_i32_e64 s[0:1], -1, v0
	v_add_u32_e32 v0, v85, v217
	v_cmp_lt_i32_e64 s[6:7], -1, v0
	v_mul_f32_e32 v1, v216, v1
	v_exp_f32_e32 v82, v1
	v_cvt_f32_u32_e32 v1, v0
	v_accvgpr_read_b32 v83, a71
	v_cvt_pk_bf16_f32 v218, v170, v171
	v_cndmask_b32_e64 v0, 0, v82, s[0:1]
	v_mul_f32_e32 v1, v216, v1
	v_exp_f32_e32 v1, v1
	v_accvgpr_read_b32 v82, a70
	v_cndmask_b32_e64 v1, 0, v1, s[6:7]
	v_pk_mul_f32 v[0:1], v[82:83], v[0:1]
	v_accvgpr_read_b32 v83, a87
	v_cvt_pk_bf16_f32 v203, v0, v1
	v_add_u32_e32 v0, v84, v190
	v_cvt_f32_u32_e32 v1, v0
	v_cmp_lt_i32_e64 s[0:1], -1, v0
	v_add_u32_e32 v0, v85, v190
	v_cmp_lt_i32_e64 s[6:7], -1, v0
	v_mul_f32_e32 v1, v216, v1
	v_exp_f32_e32 v82, v1
	v_cvt_f32_u32_e32 v1, v0
	v_cndmask_b32_e64 v0, 0, v82, s[0:1]
	v_mul_f32_e32 v1, v216, v1
	v_exp_f32_e32 v1, v1
	v_accvgpr_read_b32 v82, a86
	v_cndmask_b32_e64 v1, 0, v1, s[6:7]
	v_pk_mul_f32 v[0:1], v[82:83], v[0:1]
	v_accvgpr_read_b32 v83, a103
	v_cvt_pk_bf16_f32 v199, v0, v1
	v_add_u32_e32 v0, v84, v186
	v_cvt_f32_u32_e32 v1, v0
	v_cmp_lt_i32_e64 s[0:1], -1, v0
	v_add_u32_e32 v0, v85, v186
	v_cmp_lt_i32_e64 s[6:7], -1, v0
	v_mul_f32_e32 v1, v216, v1
	v_exp_f32_e32 v82, v1
	v_cvt_f32_u32_e32 v1, v0
	v_cndmask_b32_e64 v0, 0, v82, s[0:1]
	v_mul_f32_e32 v1, v216, v1
	v_exp_f32_e32 v1, v1
	v_accvgpr_read_b32 v82, a102
	v_cndmask_b32_e64 v1, 0, v1, s[6:7]
	v_pk_mul_f32 v[0:1], v[82:83], v[0:1]
	v_add_u32_e32 v82, v84, v180
	v_cvt_pk_bf16_f32 v195, v0, v1
	v_add_u32_e32 v0, v85, v180
	v_cvt_f32_u32_e32 v1, v0
	v_cvt_f32_u32_e32 v83, v82
	v_cmp_lt_i32_e64 s[0:1], -1, v0
	v_cvt_f32_u32_e32 v85, v86
	v_mul_f32_e32 v1, v216, v1
	v_exp_f32_e32 v1, v1
	v_mul_f32_e32 v83, v216, v83
	v_exp_f32_e32 v83, v83
	v_mul_f32_e32 v85, v216, v85
	v_cndmask_b32_e64 v1, 0, v1, s[0:1]
	v_cmp_lt_i32_e64 s[0:1], -1, v82
	v_accvgpr_read_b32 v82, a118
	v_exp_f32_e32 v87, v85
	v_cndmask_b32_e64 v0, 0, v83, s[0:1]
	v_accvgpr_read_b32 v83, a119
	v_pk_mul_f32 v[164:165], v[82:83], v[0:1]
	v_not_b32_e32 v0, 16
	v_mad_i32_i24 v89, v246, -4, v0
	v_add_u32_e32 v0, v89, v217
	v_cvt_f32_u32_e32 v1, v0
	v_add_u32_e32 v82, v88, v217
	v_cvt_f32_u32_e32 v83, v82
	v_cmp_lt_i32_e64 s[0:1], -1, v0
	v_mul_f32_e32 v1, v216, v1
	v_exp_f32_e32 v1, v1
	v_mul_f32_e32 v83, v216, v83
	v_exp_f32_e32 v83, v83
	v_cvt_pk_bf16_f32 v219, v164, v165
	v_cndmask_b32_e64 v1, 0, v1, s[0:1]
	v_cmp_lt_i32_e64 s[0:1], -1, v82
	v_accvgpr_read_b32 v82, a72
	s_nop 0
	v_cndmask_b32_e64 v0, 0, v83, s[0:1]
	v_accvgpr_read_b32 v83, a73
	v_pk_mul_f32 v[160:161], v[82:83], v[0:1]
	v_add_u32_e32 v1, v89, v190
	v_cvt_f32_u32_e32 v84, v1
	v_cmp_lt_i32_e64 s[0:1], -1, v1
	v_accvgpr_read_b32 v83, a89
	v_accvgpr_read_b32 v82, a88
	v_mul_f32_e32 v84, v216, v84
	v_exp_f32_e32 v84, v84
	v_add_u32_e32 v1, v88, v186
	v_add_u32_e32 v0, 0x15000, v174
	s_waitcnt vmcnt(7)
	ds_write_b128 v0, v[156:159]
	v_cndmask_b32_e64 v85, 0, v84, s[0:1]
	v_cmp_lt_i32_e64 s[0:1], -1, v86
	v_cvt_f32_u32_e32 v86, v1
	s_waitcnt vmcnt(6)
	ds_write_b128 v0, v[140:143] offset:4608
	v_cndmask_b32_e64 v84, 0, v87, s[0:1]
	v_add_u32_e32 v87, v89, v186
	v_pk_mul_f32 v[82:83], v[82:83], v[84:85]
	v_cvt_f32_u32_e32 v84, v87
	v_mul_f32_e32 v85, v216, v86
	v_cmp_lt_i32_e64 s[0:1], -1, v1
	v_exp_f32_e32 v86, v85
	v_mul_f32_e32 v1, v216, v84
	v_exp_f32_e32 v1, v1
	v_cmp_lt_i32_e64 s[6:7], -1, v87
	v_accvgpr_read_b32 v85, a105
	v_accvgpr_read_b32 v84, a104
	v_cndmask_b32_e64 v87, 0, v1, s[6:7]
	v_cndmask_b32_e64 v86, 0, v86, s[0:1]
	v_add_u32_e32 v1, v88, v180
	v_add_u32_e32 v89, v89, v180
	v_cvt_f32_u32_e32 v88, v1
	v_pk_mul_f32 v[84:85], v[84:85], v[86:87]
	v_cvt_f32_u32_e32 v86, v89
	v_cmp_lt_i32_e64 s[0:1], -1, v1
	v_mul_f32_e32 v87, v216, v88
	v_exp_f32_e32 v88, v87
	v_mul_f32_e32 v1, v216, v86
	v_exp_f32_e32 v1, v1
	v_cmp_lt_i32_e64 s[6:7], -1, v89
	v_accvgpr_read_b32 v87, a121
	v_accvgpr_read_b32 v86, a120
	v_cndmask_b32_e64 v89, 0, v1, s[6:7]
	v_cndmask_b32_e64 v88, 0, v88, s[0:1]
	v_pk_mul_f32 v[158:159], v[86:87], v[88:89]
	v_not_b32_e32 v1, 17
	v_not_b32_e32 v88, 18
	v_mad_i32_i24 v1, v246, -4, v1
	v_mad_i32_i24 v90, v246, -4, v88
	v_add_u32_e32 v86, v1, v217
	v_add_u32_e32 v88, v90, v217
	v_cvt_f32_u32_e32 v87, v86
	v_cvt_f32_u32_e32 v89, v88
	v_cmp_lt_i32_e64 s[0:1], -1, v86
	v_cmp_lt_i32_e64 s[6:7], -1, v88
	v_mul_f32_e32 v87, v216, v87
	v_mul_f32_e32 v86, v216, v89
	v_exp_f32_e32 v91, v87
	v_exp_f32_e32 v89, v86
	v_accvgpr_read_b32 v87, a75
	v_accvgpr_read_b32 v86, a74
	v_cndmask_b32_e64 v88, 0, v91, s[0:1]
	v_cndmask_b32_e64 v89, 0, v89, s[6:7]
	v_pk_mul_f32 v[86:87], v[86:87], v[88:89]
	v_add_u32_e32 v88, v90, v190
	v_cvt_pk_bf16_f32 v221, v86, v87
	v_add_u32_e32 v86, v1, v190
	v_cvt_f32_u32_e32 v87, v86
	v_cmp_lt_i32_e64 s[0:1], -1, v86
	v_cvt_f32_u32_e32 v86, v88
	v_cvt_pk_bf16_f32 v208, v82, v83
	v_mul_f32_e32 v87, v216, v87
	v_exp_f32_e32 v89, v87
	v_mul_f32_e32 v86, v216, v86
	v_exp_f32_e32 v86, v86
	v_add_u32_e32 v82, v1, v186
	v_cvt_f32_u32_e32 v83, v82
	v_cmp_lt_i32_e64 s[6:7], -1, v88
	v_accvgpr_read_b32 v88, a90
	v_add_u32_e32 v1, v1, v180
	v_cndmask_b32_e64 v87, 0, v86, s[6:7]
	v_cndmask_b32_e64 v86, 0, v89, s[0:1]
	v_accvgpr_read_b32 v89, a91
	v_pk_mul_f32 v[86:87], v[88:89], v[86:87]
	v_mul_f32_e32 v83, v216, v83
	v_cmp_lt_i32_e64 s[0:1], -1, v82
	v_add_u32_e32 v82, v90, v186
	v_cvt_pk_bf16_f32 v209, v86, v87
	v_exp_f32_e32 v86, v83
	v_cvt_f32_u32_e32 v83, v82
	v_cmp_lt_i32_e64 s[6:7], -1, v82
	v_accvgpr_read_b32 v87, a107
	v_cndmask_b32_e64 v82, 0, v86, s[0:1]
	v_mul_f32_e32 v83, v216, v83
	v_exp_f32_e32 v83, v83
	v_accvgpr_read_b32 v86, a106
	v_cmp_lt_i32_e64 s[0:1], -1, v1
	v_cvt_pk_bf16_f32 v204, v84, v85
	v_cndmask_b32_e64 v83, 0, v83, s[6:7]
	v_pk_mul_f32 v[82:83], v[86:87], v[82:83]
	v_accvgpr_read_b32 v85, a123
	v_cvt_pk_bf16_f32 v205, v82, v83
	v_cvt_f32_u32_e32 v82, v1
	v_add_u32_e32 v1, v90, v180
	v_cvt_f32_u32_e32 v83, v1
	v_cmp_lt_i32_e64 s[6:7], -1, v1
	v_mul_f32_e32 v82, v216, v82
	v_exp_f32_e32 v82, v82
	v_mul_f32_e32 v83, v216, v83
	v_exp_f32_e32 v83, v83
	v_not_b32_e32 v1, 23
	v_cndmask_b32_e64 v82, 0, v82, s[0:1]
	v_accvgpr_read_b32 v84, a122
	v_cndmask_b32_e64 v83, 0, v83, s[6:7]
	v_mad_i32_i24 v1, v246, -4, v1
	v_pk_mul_f32 v[82:83], v[84:85], v[82:83]
	v_add_u32_e32 v84, v1, v217
	v_cvt_f32_u32_e32 v85, v84
	v_cmp_lt_i32_e64 s[0:1], -1, v84
	v_not_b32_e32 v84, 24
	v_mad_i32_i24 v88, v246, -4, v84
	v_mul_f32_e32 v85, v216, v85
	v_add_u32_e32 v84, v88, v217
	v_exp_f32_e32 v86, v85
	v_cvt_f32_u32_e32 v85, v84
	v_cmp_lt_i32_e64 s[6:7], -1, v84
	v_accvgpr_read_b32 v87, a77
	v_cndmask_b32_e64 v84, 0, v86, s[0:1]
	v_mul_f32_e32 v85, v216, v85
	v_exp_f32_e32 v85, v85
	v_accvgpr_read_b32 v86, a76
	v_accvgpr_read_b32 v89, a79
	v_cvt_pk_bf16_f32 v213, v82, v83
	v_cndmask_b32_e64 v85, 0, v85, s[6:7]
	v_pk_mul_f32 v[84:85], v[86:87], v[84:85]
	v_accvgpr_read_b32 v87, a93
	v_cvt_pk_bf16_f32 v222, v84, v85
	v_add_u32_e32 v84, v1, v190
	v_cvt_f32_u32_e32 v85, v84
	v_cmp_lt_i32_e64 s[0:1], -1, v84
	v_add_u32_e32 v84, v88, v190
	v_cmp_lt_i32_e64 s[6:7], -1, v84
	v_mul_f32_e32 v85, v216, v85
	v_exp_f32_e32 v86, v85
	v_cvt_f32_u32_e32 v85, v84
	v_accvgpr_read_b32 v83, a43
	v_accvgpr_read_b32 v82, a42
	v_cndmask_b32_e64 v84, 0, v86, s[0:1]
	v_mul_f32_e32 v85, v216, v85
	v_exp_f32_e32 v85, v85
	v_accvgpr_read_b32 v86, a92
	s_waitcnt vmcnt(5)
	ds_write_b128 v0, v[136:139] offset:9216
	s_waitcnt vmcnt(4)
	ds_write_b128 v0, v[132:135] offset:13824
	s_waitcnt vmcnt(3)
	ds_write_b128 v0, v[128:131] offset:18432
	v_pk_mul_f32 v[138:139], v[176:177], v[82:83]
	v_cndmask_b32_e64 v85, 0, v85, s[6:7]
	v_pk_mul_f32 v[84:85], v[86:87], v[84:85]
	v_accvgpr_read_b32 v87, a109
	v_cvt_pk_bf16_f32 v210, v84, v85
	v_add_u32_e32 v84, v1, v186
	v_cvt_f32_u32_e32 v85, v84
	v_cmp_lt_i32_e64 s[0:1], -1, v84
	v_add_u32_e32 v84, v88, v186
	v_cmp_lt_i32_e64 s[6:7], -1, v84
	v_mul_f32_e32 v85, v216, v85
	v_exp_f32_e32 v86, v85
	v_cvt_f32_u32_e32 v85, v84
	v_add_u32_e32 v1, v1, v180
	v_accvgpr_read_b32 v83, a41
	v_cndmask_b32_e64 v84, 0, v86, s[0:1]
	v_mul_f32_e32 v85, v216, v85
	v_exp_f32_e32 v85, v85
	v_accvgpr_read_b32 v86, a108
	v_cmp_lt_i32_e64 s[0:1], -1, v1
	v_accvgpr_read_b32 v82, a40
	v_cndmask_b32_e64 v85, 0, v85, s[6:7]
	v_pk_mul_f32 v[84:85], v[86:87], v[84:85]
	v_accvgpr_read_b32 v87, a125
	v_cvt_pk_bf16_f32 v206, v84, v85
	v_cvt_f32_u32_e32 v84, v1
	v_add_u32_e32 v1, v88, v180
	v_cvt_f32_u32_e32 v85, v1
	v_cmp_lt_i32_e64 s[6:7], -1, v1
	v_mul_f32_e32 v84, v216, v84
	v_exp_f32_e32 v84, v84
	v_mul_f32_e32 v85, v216, v85
	v_exp_f32_e32 v85, v85
	v_not_b32_e32 v1, 25
	v_cndmask_b32_e64 v84, 0, v84, s[0:1]
	v_accvgpr_read_b32 v86, a124
	v_cndmask_b32_e64 v85, 0, v85, s[6:7]
	v_mad_i32_i24 v1, v246, -4, v1
	v_pk_mul_f32 v[84:85], v[86:87], v[84:85]
	v_add_u32_e32 v86, v1, v217
	v_cvt_f32_u32_e32 v87, v86
	v_cmp_lt_i32_e64 s[0:1], -1, v86
	v_not_b32_e32 v86, 26
	v_mad_i32_i24 v90, v246, -4, v86
	v_mul_f32_e32 v87, v216, v87
	v_add_u32_e32 v86, v90, v217
	v_exp_f32_e32 v88, v87
	v_cvt_f32_u32_e32 v87, v86
	v_cmp_lt_i32_e64 s[6:7], -1, v86
	v_pk_mul_f32 v[136:137], v[94:95], v[82:83]
	v_cndmask_b32_e64 v86, 0, v88, s[0:1]
	v_mul_f32_e32 v87, v216, v87
	v_exp_f32_e32 v87, v87
	v_accvgpr_read_b32 v88, a78
	v_accvgpr_read_b32 v83, a39
	v_accvgpr_read_b32 v82, a38
	v_cndmask_b32_e64 v87, 0, v87, s[6:7]
	v_pk_mul_f32 v[86:87], v[88:89], v[86:87]
	v_accvgpr_read_b32 v89, a95
	v_cvt_pk_bf16_f32 v223, v86, v87
	v_add_u32_e32 v86, v1, v190
	v_cvt_f32_u32_e32 v87, v86
	v_cmp_lt_i32_e64 s[0:1], -1, v86
	v_add_u32_e32 v86, v90, v190
	v_cmp_lt_i32_e64 s[6:7], -1, v86
	v_mul_f32_e32 v87, v216, v87
	v_exp_f32_e32 v88, v87
	v_cvt_f32_u32_e32 v87, v86
	v_pk_mul_f32 v[134:135], v[92:93], v[82:83]
	v_accvgpr_read_b32 v83, a37
	v_cndmask_b32_e64 v86, 0, v88, s[0:1]
	v_mul_f32_e32 v87, v216, v87
	v_exp_f32_e32 v87, v87
	v_accvgpr_read_b32 v88, a94
	v_accvgpr_read_b32 v82, a36
	v_accvgpr_read_b32 v157, a35
	v_cndmask_b32_e64 v87, 0, v87, s[6:7]
	v_pk_mul_f32 v[86:87], v[88:89], v[86:87]
	v_accvgpr_read_b32 v89, a111
	v_cvt_pk_bf16_f32 v211, v86, v87
	v_add_u32_e32 v86, v1, v186
	v_cvt_f32_u32_e32 v87, v86
	v_cmp_lt_i32_e64 s[0:1], -1, v86
	v_add_u32_e32 v86, v90, v186
	v_cmp_lt_i32_e64 s[6:7], -1, v86
	v_mul_f32_e32 v87, v216, v87
	v_exp_f32_e32 v88, v87
	v_cvt_f32_u32_e32 v87, v86
	v_add_u32_e32 v1, v1, v180
	v_accvgpr_read_b32 v156, a34
	v_cndmask_b32_e64 v86, 0, v88, s[0:1]
	v_mul_f32_e32 v87, v216, v87
	v_exp_f32_e32 v87, v87
	v_accvgpr_read_b32 v88, a110
	v_cmp_lt_i32_e64 s[0:1], -1, v1
	s_waitcnt vmcnt(2)
	ds_write_b128 v0, v[148:151] offset:23040
	s_waitcnt vmcnt(1)
	ds_write_b128 v0, v[152:155] offset:27648
	s_waitcnt vmcnt(0)
	ds_write_b128 v0, v[144:147] offset:32256
	v_cndmask_b32_e64 v87, 0, v87, s[6:7]
	v_pk_mul_f32 v[86:87], v[88:89], v[86:87]
	v_accvgpr_read_b32 v89, a127
	v_cvt_pk_bf16_f32 v207, v86, v87
	v_add_u32_e32 v86, v90, v180
	v_cvt_f32_u32_e32 v87, v1
	v_cvt_f32_u32_e32 v1, v86
	v_cmp_lt_i32_e64 s[6:7], -1, v86
	v_accvgpr_read_b32 v90, a210
	v_mul_f32_e32 v87, v216, v87
	v_mul_f32_e32 v1, v216, v1
	v_exp_f32_e32 v88, v87
	v_exp_f32_e32 v1, v1
	v_accvgpr_read_b32 v91, a211
	v_pk_mul_f32 v[132:133], v[90:91], v[82:83]
	v_cndmask_b32_e64 v86, 0, v88, s[0:1]
	v_cndmask_b32_e64 v87, 0, v1, s[6:7]
	v_accvgpr_read_b32 v88, a126
	v_pk_mul_f32 v[86:87], v[88:89], v[86:87]
	v_accvgpr_read_b32 v88, a208
	v_accvgpr_read_b32 v83, a13
	v_accvgpr_read_b32 v82, a12
	v_accvgpr_read_b32 v89, a209
	v_pk_mul_f32 v[130:131], v[88:89], v[156:157]
	v_pk_mul_f32 v[156:157], v[178:179], v[82:83]
	v_accvgpr_read_b32 v83, a11
	v_accvgpr_read_b32 v82, a10
	v_pk_mul_f32 v[154:155], v[176:177], v[82:83]
	v_accvgpr_read_b32 v83, a9
	v_accvgpr_read_b32 v82, a8
	v_pk_mul_f32 v[152:153], v[94:95], v[82:83]
	v_accvgpr_read_b32 v83, a7
	v_accvgpr_read_b32 v82, a6
	v_pk_mul_f32 v[150:151], v[92:93], v[82:83]
	v_accvgpr_read_b32 v83, a5
	v_accvgpr_read_b32 v82, a4
	v_pk_mul_f32 v[148:149], v[90:91], v[82:83]
	v_accvgpr_read_b32 v83, a3
	v_accvgpr_read_b32 v82, a2
	v_cvt_pk_bf16_f32 v215, v86, v87
	v_accvgpr_read_b32 v86, a206
	v_pk_mul_f32 v[146:147], v[88:89], v[82:83]
	v_accvgpr_read_b32 v83, a1
	v_accvgpr_read_b32 v87, a207
	v_accvgpr_read_b32 v82, a0
	v_pk_mul_f32 v[144:145], v[86:87], v[82:83]
	v_accvgpr_read_b32 v83, a29
	v_accvgpr_read_b32 v82, a28
	v_cvt_pk_bf16_f32 v216, v172, v173
	v_pk_mul_f32 v[172:173], v[178:179], v[82:83]
	v_accvgpr_read_b32 v83, a27
	v_accvgpr_read_b32 v82, a26
	v_pk_mul_f32 v[170:171], v[176:177], v[82:83]
	v_accvgpr_read_b32 v83, a25
	v_accvgpr_read_b32 v82, a24
	v_cvt_pk_bf16_f32 v217, v168, v169
	v_pk_mul_f32 v[168:169], v[94:95], v[82:83]
	v_accvgpr_read_b32 v83, a23
	v_accvgpr_read_b32 v82, a22
	v_pk_mul_f32 v[166:167], v[92:93], v[82:83]
	v_accvgpr_read_b32 v83, a21
	v_accvgpr_read_b32 v82, a20
	v_pk_mul_f32 v[164:165], v[90:91], v[82:83]
	v_accvgpr_read_b32 v83, a19
	v_accvgpr_read_b32 v82, a18
	v_pk_mul_f32 v[162:163], v[88:89], v[82:83]
	v_accvgpr_read_b32 v83, a17
	v_accvgpr_read_b32 v82, a16
	v_cvt_pk_bf16_f32 v220, v160, v161
	v_cvt_pk_bf16_f32 v214, v84, v85
	v_accvgpr_read_b32 v85, a33
	v_pk_mul_f32 v[160:161], v[86:87], v[82:83]
	v_accvgpr_read_b32 v83, a61
	v_accvgpr_read_b32 v82, a60
	v_accvgpr_read_b32 v180, a220
	v_accvgpr_read_b32 v84, a32
	v_pk_mul_f32 v[188:189], v[178:179], v[82:83]
	v_accvgpr_read_b32 v83, a59
	v_accvgpr_read_b32 v82, a58
	v_accvgpr_read_b32 v181, a221
	v_pk_mul_f32 v[128:129], v[86:87], v[84:85]
	v_accvgpr_read_b32 v85, a15
	v_accvgpr_read_b32 v84, a14
	v_pk_mul_f32 v[186:187], v[176:177], v[82:83]
	v_accvgpr_read_b32 v83, a57
	v_accvgpr_read_b32 v82, a56
	v_cvt_pk_bf16_f32 v212, v158, v159
	v_pk_mul_f32 v[158:159], v[180:181], v[84:85]
	v_accvgpr_read_b32 v85, a31
	v_accvgpr_read_b32 v84, a30
	v_pk_mul_f32 v[184:185], v[94:95], v[82:83]
	v_accvgpr_read_b32 v83, a55
	v_accvgpr_read_b32 v82, a54
	v_accvgpr_read_b32 v143, a47
	v_accvgpr_read_b32 v142, a46
	v_pk_mul_f32 v[174:175], v[180:181], v[84:85]
	v_accvgpr_read_b32 v85, a63
	v_accvgpr_read_b32 v84, a62
	v_pk_mul_f32 v[182:183], v[92:93], v[82:83]
	v_accvgpr_read_b32 v83, a53
	v_accvgpr_read_b32 v82, a52
	v_accvgpr_read_b32 v141, a45
	v_accvgpr_read_b32 v140, a44
	v_pk_mul_f32 v[142:143], v[180:181], v[142:143]
	v_pk_mul_f32 v[190:191], v[180:181], v[84:85]
	v_pk_mul_f32 v[180:181], v[90:91], v[82:83]
	v_accvgpr_read_b32 v83, a51
	v_accvgpr_read_b32 v82, a50
	v_pk_mul_f32 v[140:141], v[178:179], v[140:141]
	v_pk_mul_f32 v[178:179], v[88:89], v[82:83]
	v_accvgpr_read_b32 v83, a49
	v_mov_b32_e32 v1, s17
	s_mov_b32 s0, 0xfffffdf
	v_accvgpr_read_b32 v82, a48
	v_bitop3_b32 v1, v248, s0, v1 bitop3:0xc8
	v_pk_mul_f32 v[176:177], v[86:87], v[82:83]
	v_mul_lo_u32 v1, v1, s27
	v_lshlrev_b32_e32 v82, 4, v246
	v_add3_u32 v83, v1, v82, s59
	v_or_b32_e32 v1, 32, v249
	v_mul_lo_u32 v1, v1, s27
	v_add3_u32 v84, v1, v82, s59
	v_and_b32_e32 v1, 31, v248
	v_lshlrev_b32_e32 v248, 3, v246
	v_mul_u32_u24_e32 v82, 0x90, v1
	v_or_b32_e32 v82, v82, v248
	v_add_u32_e32 v85, 0x10800, v82
	s_waitcnt lgkmcnt(0)
	s_barrier
	v_add_u32_e32 v82, v85, v248
	ds_read2_b64 v[86:89], v85 offset1:2
	v_accvgpr_write_b32 a191, v143
	v_accvgpr_write_b32 a190, v142
	v_accvgpr_write_b32 a189, v141
	v_accvgpr_write_b32 a188, v140
	v_accvgpr_write_b32 a187, v139
	v_accvgpr_write_b32 a186, v138
	v_accvgpr_write_b32 a185, v137
	v_accvgpr_write_b32 a184, v136
	v_accvgpr_write_b32 a183, v135
	v_accvgpr_write_b32 a182, v134
	v_accvgpr_write_b32 a181, v133
	v_accvgpr_write_b32 a180, v132
	v_accvgpr_write_b32 a179, v131
	v_accvgpr_write_b32 a178, v130
	v_accvgpr_write_b32 a177, v129
	v_accvgpr_write_b32 a176, v128
	v_add_u32_e32 v94, 0x1000, v85
	v_accvgpr_write_b32 a175, v159
	s_waitcnt lgkmcnt(0)
	v_mfma_f32_32x32x16_bf16 a[176:191], v[86:89], v[200:203], a[176:191]
	ds_read2_b64 v[86:89], v94 offset0:64 offset1:66
	v_accvgpr_write_b32 a174, v158
	v_accvgpr_write_b32 a173, v157
	v_accvgpr_write_b32 a172, v156
	v_accvgpr_write_b32 a171, v155
	v_accvgpr_write_b32 a170, v154
	v_accvgpr_write_b32 a169, v153
	v_accvgpr_write_b32 a168, v152
	v_accvgpr_write_b32 a167, v151
	v_accvgpr_write_b32 a166, v150
	v_accvgpr_write_b32 a165, v149
	v_accvgpr_write_b32 a164, v148
	v_accvgpr_write_b32 a163, v147
	v_accvgpr_write_b32 a162, v146
	v_accvgpr_write_b32 a161, v145
	v_accvgpr_write_b32 a160, v144
	v_add_u32_e32 v95, 0x2000, v85
	v_accvgpr_write_b32 a144, v160
	s_waitcnt lgkmcnt(0)
	v_mfma_f32_32x32x16_bf16 a[160:175], v[86:89], v[200:203], a[160:175]
	ds_read2_b64 v[86:89], v95 offset0:128 offset1:130
	v_accvgpr_write_b32 a145, v161
	v_accvgpr_write_b32 a146, v162
	v_accvgpr_write_b32 a147, v163
	v_accvgpr_write_b32 a148, v164
	v_accvgpr_write_b32 a149, v165
	v_accvgpr_write_b32 a150, v166
	v_accvgpr_write_b32 a151, v167
	v_accvgpr_write_b32 a152, v168
	v_accvgpr_write_b32 a153, v169
	v_accvgpr_write_b32 a154, v170
	v_accvgpr_write_b32 a155, v171
	v_accvgpr_write_b32 a156, v172
	v_accvgpr_write_b32 a157, v173
	v_accvgpr_write_b32 a158, v174
	v_accvgpr_write_b32 a159, v175
	v_add_u32_e32 v144, 0x3000, v85
	v_accvgpr_write_b32 a128, v176
	s_waitcnt lgkmcnt(0)
	v_mfma_f32_32x32x16_bf16 a[144:159], v[86:89], v[200:203], a[144:159]
	ds_read2_b64 v[86:89], v144 offset0:192 offset1:194
	v_accvgpr_write_b32 a129, v177
	v_accvgpr_write_b32 a130, v178
	v_accvgpr_write_b32 a131, v179
	v_accvgpr_write_b32 a132, v180
	v_accvgpr_write_b32 a133, v181
	v_accvgpr_write_b32 a134, v182
	v_accvgpr_write_b32 a135, v183
	v_accvgpr_write_b32 a136, v184
	v_accvgpr_write_b32 a137, v185
	v_accvgpr_write_b32 a138, v186
	v_accvgpr_write_b32 a139, v187
	v_accvgpr_write_b32 a140, v188
	v_accvgpr_write_b32 a141, v189
	v_accvgpr_write_b32 a142, v190
	v_accvgpr_write_b32 a143, v191
	v_accvgpr_mov_b32 a0, a226
	v_accvgpr_write_b32 a32, v50
	s_waitcnt lgkmcnt(0)
	v_mfma_f32_32x32x16_bf16 a[128:143], v[86:89], v[200:203], a[128:143]
	ds_read2_b64 v[86:89], v85 offset0:4 offset1:6
	v_accvgpr_write_b32 a111, v33
	v_accvgpr_mov_b32 a1, a227
	v_accvgpr_mov_b32 a2, a228
	v_accvgpr_mov_b32 a3, a229
	v_accvgpr_mov_b32 a4, a230
	v_accvgpr_mov_b32 a5, a231
	s_waitcnt lgkmcnt(0)
	v_mfma_f32_32x32x16_bf16 a[176:191], v[86:89], v[220:223], a[176:191]
	ds_read2_b64 v[86:89], v94 offset0:68 offset1:70
	v_accvgpr_mov_b32 a6, a232
	v_accvgpr_mov_b32 a7, a233
	v_accvgpr_mov_b32 a8, a234
	v_accvgpr_mov_b32 a9, a235
	v_accvgpr_mov_b32 a10, a236
	v_accvgpr_mov_b32 a11, a237
	s_waitcnt lgkmcnt(0)
	v_mfma_f32_32x32x16_bf16 a[160:175], v[86:89], v[220:223], a[160:175]
	ds_read2_b64 v[86:89], v95 offset0:132 offset1:134
	v_accvgpr_mov_b32 a12, a238
	v_accvgpr_mov_b32 a13, a239
	v_accvgpr_mov_b32 a14, a240
	v_accvgpr_mov_b32 a15, a241
	v_accvgpr_write_b32 a33, v51
	v_accvgpr_write_b32 a34, v52
	s_waitcnt lgkmcnt(0)
	v_mfma_f32_32x32x16_bf16 a[144:159], v[86:89], v[220:223], a[144:159]
	ds_read2_b64 v[86:89], v144 offset0:196 offset1:198
	v_accvgpr_write_b32 a35, v53
	v_accvgpr_write_b32 a36, v54
	v_accvgpr_write_b32 a37, v55
	v_accvgpr_write_b32 a38, v56
	v_accvgpr_write_b32 a39, v57
	v_accvgpr_write_b32 a40, v58
	s_waitcnt lgkmcnt(0)
	v_mfma_f32_32x32x16_bf16 a[128:143], v[86:89], v[220:223], a[128:143]
	ds_read2_b64 v[86:89], v85 offset0:8 offset1:10
	v_accvgpr_write_b32 a41, v59
	v_accvgpr_write_b32 a42, v60
	v_accvgpr_write_b32 a43, v61
	v_accvgpr_write_b32 a44, v62
	v_accvgpr_write_b32 a45, v63
	v_accvgpr_write_b32 a46, v64
	s_waitcnt lgkmcnt(0)
	v_mfma_f32_32x32x16_bf16 a[176:191], v[86:89], v[196:199], a[176:191]
	ds_read2_b64 v[86:89], v94 offset0:72 offset1:74
	v_accvgpr_write_b32 a47, v65
	v_accvgpr_write_b32 a110, v32
	v_accvgpr_write_b32 a109, v31
	v_accvgpr_write_b32 a108, v30
	v_accvgpr_write_b32 a107, v29
	v_accvgpr_write_b32 a106, v28
	s_waitcnt lgkmcnt(0)
	v_mfma_f32_32x32x16_bf16 a[160:175], v[86:89], v[196:199], a[160:175]
	ds_read2_b64 v[86:89], v95 offset0:136 offset1:138
	v_accvgpr_write_b32 a105, v27
	v_accvgpr_write_b32 a104, v26
	v_accvgpr_write_b32 a103, v25
	v_accvgpr_write_b32 a102, v24
	v_accvgpr_write_b32 a101, v23
	v_accvgpr_write_b32 a100, v22
	s_waitcnt lgkmcnt(0)
	v_mfma_f32_32x32x16_bf16 a[144:159], v[86:89], v[196:199], a[144:159]
	ds_read2_b64 v[86:89], v144 offset0:200 offset1:202
	v_accvgpr_write_b32 a99, v21
	v_accvgpr_write_b32 a98, v20
	v_accvgpr_write_b32 a97, v19
	v_accvgpr_write_b32 a96, v18
	v_accvgpr_write_b32 a16, v112
	v_accvgpr_write_b32 a95, v49
	s_waitcnt lgkmcnt(0)
	v_mfma_f32_32x32x16_bf16 a[128:143], v[86:89], v[196:199], a[128:143]
	ds_read2_b64 v[86:89], v85 offset0:12 offset1:14
	v_accvgpr_write_b32 a64, v66
	v_accvgpr_write_b32 a127, v17
	v_accvgpr_write_b32 a17, v113
	v_accvgpr_write_b32 a18, v114
	v_accvgpr_write_b32 a19, v115
	v_accvgpr_write_b32 a20, v116
	s_waitcnt lgkmcnt(0)
	v_mfma_f32_32x32x16_bf16 a[176:191], v[86:89], v[208:211], a[176:191]
	ds_read2_b64 v[86:89], v94 offset0:76 offset1:78
	v_accvgpr_write_b32 a21, v117
	v_accvgpr_write_b32 a22, v118
	v_accvgpr_write_b32 a23, v119
	v_accvgpr_write_b32 a24, v120
	v_accvgpr_write_b32 a25, v121
	v_accvgpr_write_b32 a26, v122
	s_waitcnt lgkmcnt(0)
	v_mfma_f32_32x32x16_bf16 a[160:175], v[86:89], v[208:211], a[160:175]
	ds_read2_b64 v[86:89], v95 offset0:140 offset1:142
	v_accvgpr_write_b32 a27, v123
	v_accvgpr_write_b32 a28, v124
	v_accvgpr_write_b32 a29, v125
	v_accvgpr_write_b32 a30, v126
	v_accvgpr_write_b32 a31, v127
	v_accvgpr_write_b32 a94, v48
	s_waitcnt lgkmcnt(0)
	v_mfma_f32_32x32x16_bf16 a[144:159], v[86:89], v[208:211], a[144:159]
	ds_read2_b64 v[86:89], v144 offset0:204 offset1:206
	v_accvgpr_write_b32 a93, v47
	v_accvgpr_write_b32 a92, v46
	v_accvgpr_write_b32 a91, v45
	v_accvgpr_write_b32 a90, v44
	v_accvgpr_write_b32 a89, v43
	v_accvgpr_write_b32 a88, v42
	s_waitcnt lgkmcnt(0)
	v_mfma_f32_32x32x16_bf16 a[128:143], v[86:89], v[208:211], a[128:143]
	ds_read_b128 v[86:89], v83
	ds_read_b128 v[90:93], v82
	ds_read_b128 v[128:131], v83 offset:32
	ds_read_b128 v[132:135], v82 offset:32
	ds_read_b128 v[136:139], v84
	ds_read_b128 v[140:143], v84 offset:32
	ds_read_b128 v[50:53], v82 offset:4608
	ds_read_b128 v[54:57], v82 offset:4640
	ds_read_b128 v[18:21], v82 offset:13824
	ds_read_b128 v[22:25], v82 offset:13856
	v_accvgpr_write_b32 a87, v41
	s_waitcnt lgkmcnt(8)
	v_mfma_f32_32x32x16_bf16 a[0:15], v[86:89], v[90:93], a[0:15]
	v_accvgpr_write_b32 a86, v40
	v_accvgpr_write_b32 a85, v39
	v_accvgpr_write_b32 a84, v38
	v_accvgpr_write_b32 a83, v37
	v_accvgpr_write_b32 a82, v36
	v_accvgpr_write_b32 a81, v35
	v_accvgpr_write_b32 a80, v34
	s_waitcnt lgkmcnt(5)
	v_mfma_f32_32x32x16_bf16 a[32:47], v[136:139], v[90:93], a[32:47]
	ds_read_b128 v[34:37], v82 offset:9216
	ds_read_b128 v[38:41], v82 offset:9248
	v_accvgpr_write_b32 a65, v67
	v_accvgpr_write_b32 a66, v68
	v_accvgpr_write_b32 a67, v69
	v_accvgpr_write_b32 a68, v70
	v_accvgpr_write_b32 a69, v71
	v_accvgpr_write_b32 a70, v72
	v_accvgpr_write_b32 a71, v73
	v_accvgpr_write_b32 a72, v74
	v_accvgpr_write_b32 a73, v75
	v_accvgpr_write_b32 a74, v76
	v_accvgpr_write_b32 a75, v77
	v_accvgpr_write_b32 a76, v78
	v_accvgpr_write_b32 a77, v79
	v_accvgpr_write_b32 a78, v80
	v_accvgpr_write_b32 a79, v81
	v_accvgpr_write_b32 a126, v16
	v_accvgpr_write_b32 a125, v15
	v_accvgpr_write_b32 a124, v14
	v_accvgpr_write_b32 a123, v13
	v_accvgpr_write_b32 a122, v12
	v_accvgpr_write_b32 a121, v11
	v_accvgpr_write_b32 a120, v10
	v_accvgpr_write_b32 a119, v9
	v_accvgpr_write_b32 a118, v8
	v_accvgpr_write_b32 a117, v7
	v_accvgpr_write_b32 a116, v6
	v_accvgpr_write_b32 a115, v5
	v_accvgpr_write_b32 a114, v4
	v_accvgpr_write_b32 a113, v3
	v_accvgpr_write_b32 a112, v2
	s_waitcnt lgkmcnt(5)
	v_mfma_f32_32x32x16_bf16 a[16:31], v[86:89], v[50:53], a[16:31]
	v_accvgpr_write_b32 a48, v96
	v_accvgpr_write_b32 a49, v97
	v_accvgpr_write_b32 a50, v98
	v_accvgpr_write_b32 a51, v99
	v_accvgpr_write_b32 a52, v100
	v_accvgpr_write_b32 a53, v101
	v_accvgpr_write_b32 a54, v102
	v_mfma_f32_32x32x16_bf16 a[80:95], v[136:139], v[50:53], a[80:95]
	v_accvgpr_write_b32 a55, v103
	v_accvgpr_write_b32 a56, v104
	v_accvgpr_write_b32 a57, v105
	v_accvgpr_write_b32 a58, v106
	v_accvgpr_write_b32 a59, v107
	v_accvgpr_write_b32 a60, v108
	v_accvgpr_write_b32 a61, v109
	s_waitcnt lgkmcnt(3)
	v_mfma_f32_32x32x16_bf16 a[64:79], v[86:89], v[18:21], a[64:79]
	v_accvgpr_write_b32 a62, v110
	v_accvgpr_write_b32 a63, v111
	ds_read_b128 v[2:5], v83 offset:64
	ds_read_b128 v[6:9], v82 offset:64
	ds_read_b128 v[10:13], v83 offset:96
	ds_read_b128 v[14:17], v82 offset:96
	v_accvgpr_read_b32 v198, a201
	v_accvgpr_read_b32 v197, a197
	v_accvgpr_read_b32 v196, a196
	v_mfma_f32_32x32x16_bf16 a[112:127], v[136:139], v[18:21], a[112:127]
	s_waitcnt lgkmcnt(5)
	v_mfma_f32_32x32x16_bf16 a[48:63], v[86:89], v[34:37], a[48:63]
	v_mfma_f32_32x32x16_bf16 a[96:111], v[136:139], v[34:37], a[96:111]
	v_mfma_f32_32x32x16_bf16 a[0:15], v[128:131], v[132:135], a[0:15]
	v_mfma_f32_32x32x16_bf16 a[32:47], v[140:143], v[132:135], a[32:47]
	v_accvgpr_read_b32 v132, a224
	v_accvgpr_read_b32 v133, a225
	v_mfma_f32_32x32x16_bf16 a[16:31], v[128:131], v[54:57], a[16:31]
	v_mfma_f32_32x32x16_bf16 a[80:95], v[140:143], v[54:57], a[80:95]
	v_mfma_f32_32x32x16_bf16 a[64:79], v[128:131], v[22:25], a[64:79]
	v_mfma_f32_32x32x16_bf16 a[112:127], v[140:143], v[22:25], a[112:127]
	ds_read_b128 v[18:21], v84 offset:64
	ds_read_b128 v[22:25], v84 offset:96
	s_waitcnt lgkmcnt(6)
	v_mfma_f32_32x32x16_bf16 a[48:63], v[128:131], v[38:41], a[48:63]
	v_mfma_f32_32x32x16_bf16 a[96:111], v[140:143], v[38:41], a[96:111]
	s_waitcnt lgkmcnt(4)
	v_mfma_f32_32x32x16_bf16 a[0:15], v[2:5], v[6:9], a[0:15]
	s_waitcnt lgkmcnt(1)
	v_mfma_f32_32x32x16_bf16 a[32:47], v[18:21], v[6:9], a[32:47]
	ds_read_b128 v[6:9], v82 offset:4672
	ds_read_b128 v[26:29], v82 offset:4704
	s_waitcnt lgkmcnt(1)
	v_mfma_f32_32x32x16_bf16 a[16:31], v[2:5], v[6:9], a[16:31]
	v_mfma_f32_32x32x16_bf16 a[80:95], v[18:21], v[6:9], a[80:95]
	ds_read_b128 v[6:9], v82 offset:9280
	ds_read_b128 v[30:33], v82 offset:9312
	s_waitcnt lgkmcnt(1)
	v_mfma_f32_32x32x16_bf16 a[48:63], v[2:5], v[6:9], a[48:63]
	v_mfma_f32_32x32x16_bf16 a[96:111], v[18:21], v[6:9], a[96:111]
	ds_read_b128 v[6:9], v82 offset:13888
	ds_read_b128 v[34:37], v82 offset:13920
	s_waitcnt lgkmcnt(1)
	v_mfma_f32_32x32x16_bf16 a[64:79], v[2:5], v[6:9], a[64:79]
	v_mfma_f32_32x32x16_bf16 a[112:127], v[18:21], v[6:9], a[112:127]
	global_load_dwordx4 v[2:5], v[250:251], off offset:128
	global_load_dwordx4 v[6:9], v[252:253], off offset:128
	v_accvgpr_read_b32 v253, a193
	v_mfma_f32_32x32x16_bf16 a[0:15], v[10:13], v[14:17], a[0:15]
	v_mfma_f32_32x32x16_bf16 a[32:47], v[22:25], v[14:17], a[32:47]
	v_mfma_f32_32x32x16_bf16 a[16:31], v[10:13], v[26:29], a[16:31]
	v_mfma_f32_32x32x16_bf16 a[80:95], v[22:25], v[26:29], a[80:95]
	global_load_dwordx4 v[14:17], v[226:227], off offset:128
	global_load_dwordx4 v[18:21], v[224:225], off offset:128
	global_load_dwordx4 v[26:29], v[232:233], off offset:128
	global_load_dwordx4 v[38:41], v[234:235], off offset:128
	global_load_dwordx4 v[42:45], v[236:237], off offset:128
	global_load_dwordx4 v[46:49], v[238:239], off offset:128
	global_load_dwordx4 v[50:53], v[240:241], off offset:128
	global_load_dwordx4 v[54:57], v[242:243], off offset:128
	global_load_dwordx4 v[58:61], v[244:245], off offset:128
	global_load_dwordx4 v[62:65], v[228:229], off offset:128
	s_waitcnt lgkmcnt(0)
	s_barrier
	s_waitcnt vmcnt(11)
	ds_write_b128 v231, v[2:5]
	s_waitcnt vmcnt(10)
	ds_write_b128 v231, v[6:9] offset:4608
	s_waitcnt vmcnt(9)
	ds_write_b128 v231, v[14:17] offset:9216
	s_waitcnt vmcnt(8)
	ds_write_b128 v231, v[18:21] offset:13824
	s_waitcnt vmcnt(7)
	ds_write_b128 v0, v[26:29]
	s_waitcnt vmcnt(6)
	ds_write_b128 v0, v[38:41] offset:4608
	s_waitcnt vmcnt(5)
	ds_write_b128 v0, v[42:45] offset:9216
	v_mfma_f32_32x32x16_bf16 a[48:63], v[10:13], v[30:33], a[48:63]
	s_waitcnt vmcnt(4)
	ds_write_b128 v0, v[46:49] offset:13824
	s_waitcnt vmcnt(3)
	ds_write_b128 v0, v[50:53] offset:18432
	s_waitcnt vmcnt(2)
	ds_write_b128 v0, v[54:57] offset:23040
	s_waitcnt vmcnt(1)
	ds_write_b128 v0, v[58:61] offset:27648
	s_waitcnt vmcnt(0)
	ds_write_b128 v0, v[62:65] offset:32256
	s_waitcnt lgkmcnt(0)
	s_barrier
	v_mfma_f32_32x32x16_bf16 a[96:111], v[22:25], v[30:33], a[96:111]
	v_mfma_f32_32x32x16_bf16 a[64:79], v[10:13], v[34:37], a[64:79]
	v_mfma_f32_32x32x16_bf16 a[112:127], v[22:25], v[34:37], a[112:127]
	ds_read2_b64 v[2:5], v85 offset1:2
	ds_read2_b64 v[6:9], v85 offset0:4 offset1:6
	v_ashrrev_i32_e32 v0, 1, v249
	v_and_b32_e32 v0, 0xffffffe0, v0
	s_add_u32 s0, s8, s12
	s_waitcnt lgkmcnt(1)
	v_mfma_f32_32x32x16_bf16 a[176:191], v[2:5], v[192:195], a[176:191]
	ds_read2_b64 v[2:5], v94 offset0:64 offset1:66
	s_addc_u32 s1, s9, s13
	v_accvgpr_read_b32 v249, a193
	s_add_u32 s12, s12, 0x80
	s_addc_u32 s13, s13, 0
	s_add_u32 s4, s4, 0x100
	s_addc_u32 s5, s5, 0
	s_waitcnt lgkmcnt(1)
	v_mfma_f32_32x32x16_bf16 a[176:191], v[6:9], v[204:207], a[176:191]
	s_add_u32 s19, s19, 0x100
	s_addc_u32 s20, s20, 0
	v_accvgpr_read_b32 v128, a192
	s_cmpk_eq_i32 s12, 0x800
	s_waitcnt lgkmcnt(0)
	v_mfma_f32_32x32x16_bf16 a[160:175], v[2:5], v[192:195], a[160:175]
	ds_read2_b64 v[2:5], v95 offset0:128 offset1:130
	s_waitcnt lgkmcnt(0)
	v_mfma_f32_32x32x16_bf16 a[144:159], v[2:5], v[192:195], a[144:159]
	ds_read2_b64 v[2:5], v144 offset0:192 offset1:194
	s_waitcnt lgkmcnt(0)
	v_mfma_f32_32x32x16_bf16 a[128:143], v[2:5], v[192:195], a[128:143]
	ds_read2_b64 v[2:5], v94 offset0:68 offset1:70
	v_accvgpr_read_b32 v193, a198
	v_accvgpr_read_b32 v192, a195
	s_waitcnt lgkmcnt(0)
	v_mfma_f32_32x32x16_bf16 a[160:175], v[2:5], v[204:207], a[160:175]
	ds_read2_b64 v[2:5], v95 offset0:132 offset1:134
	s_waitcnt lgkmcnt(0)
	v_mfma_f32_32x32x16_bf16 a[144:159], v[2:5], v[204:207], a[144:159]
	ds_read2_b64 v[2:5], v144 offset0:196 offset1:198
	s_waitcnt lgkmcnt(0)
	v_mfma_f32_32x32x16_bf16 a[128:143], v[2:5], v[204:207], a[128:143]
	ds_read2_b64 v[2:5], v85 offset0:8 offset1:10
	s_waitcnt lgkmcnt(0)
	v_mfma_f32_32x32x16_bf16 a[176:191], v[2:5], v[216:219], a[176:191]
	ds_read2_b64 v[2:5], v94 offset0:72 offset1:74
	s_waitcnt lgkmcnt(0)
	v_mfma_f32_32x32x16_bf16 a[160:175], v[2:5], v[216:219], a[160:175]
	ds_read2_b64 v[2:5], v95 offset0:136 offset1:138
	s_waitcnt lgkmcnt(0)
	v_mfma_f32_32x32x16_bf16 a[144:159], v[2:5], v[216:219], a[144:159]
	ds_read2_b64 v[2:5], v144 offset0:200 offset1:202
	s_waitcnt lgkmcnt(0)
	v_mfma_f32_32x32x16_bf16 a[128:143], v[2:5], v[216:219], a[128:143]
	ds_read2_b64 v[2:5], v85 offset0:12 offset1:14
	s_waitcnt lgkmcnt(0)
	v_mfma_f32_32x32x16_bf16 a[176:191], v[2:5], v[212:215], a[176:191]
	ds_read2_b64 v[2:5], v94 offset0:76 offset1:78
	s_waitcnt lgkmcnt(0)
	v_mfma_f32_32x32x16_bf16 a[160:175], v[2:5], v[212:215], a[160:175]
	ds_read2_b64 v[2:5], v95 offset0:140 offset1:142
	s_waitcnt lgkmcnt(0)
	v_mfma_f32_32x32x16_bf16 a[144:159], v[2:5], v[212:215], a[144:159]
	ds_read2_b64 v[2:5], v144 offset0:204 offset1:206
	s_waitcnt lgkmcnt(0)
	v_mfma_f32_32x32x16_bf16 a[128:143], v[2:5], v[212:215], a[128:143]
	ds_read_b128 v[2:5], v83
	ds_read_b128 v[6:9], v83 offset:32
	ds_read_b128 v[10:13], v82
	ds_read_b128 v[14:17], v82 offset:32
	ds_read_b128 v[18:21], v84
	ds_read_b128 v[22:25], v84 offset:32
	s_waitcnt lgkmcnt(3)
	v_mfma_f32_32x32x16_bf16 a[0:15], v[2:5], v[10:13], a[0:15]
	s_waitcnt lgkmcnt(1)
	v_mfma_f32_32x32x16_bf16 a[32:47], v[18:21], v[10:13], a[32:47]
	ds_read_b128 v[10:13], v82 offset:4608
	s_waitcnt lgkmcnt(0)
	v_mfma_f32_32x32x16_bf16 a[16:31], v[2:5], v[10:13], a[16:31]
	v_mfma_f32_32x32x16_bf16 a[80:95], v[18:21], v[10:13], a[80:95]
	ds_read_b128 v[10:13], v82 offset:9216
	s_waitcnt lgkmcnt(0)
	v_mfma_f32_32x32x16_bf16 a[48:63], v[2:5], v[10:13], a[48:63]
	v_mfma_f32_32x32x16_bf16 a[96:111], v[18:21], v[10:13], a[96:111]
	ds_read_b128 v[10:13], v82 offset:13824
	s_waitcnt lgkmcnt(0)
	v_mfma_f32_32x32x16_bf16 a[64:79], v[2:5], v[10:13], a[64:79]
	ds_read_b128 v[2:5], v82 offset:4640
	s_waitcnt lgkmcnt(0)
	v_mfma_f32_32x32x16_bf16 a[16:31], v[6:9], v[2:5], a[16:31]
	v_mfma_f32_32x32x16_bf16 a[80:95], v[22:25], v[2:5], a[80:95]
	ds_read_b128 v[2:5], v82 offset:9248
	v_mfma_f32_32x32x16_bf16 a[112:127], v[18:21], v[10:13], a[112:127]
	s_waitcnt lgkmcnt(0)
	v_mfma_f32_32x32x16_bf16 a[48:63], v[6:9], v[2:5], a[48:63]
	v_mfma_f32_32x32x16_bf16 a[96:111], v[22:25], v[2:5], a[96:111]
	ds_read_b128 v[2:5], v82 offset:13856
	v_mfma_f32_32x32x16_bf16 a[0:15], v[6:9], v[14:17], a[0:15]
	v_mfma_f32_32x32x16_bf16 a[32:47], v[22:25], v[14:17], a[32:47]
	v_accvgpr_read_b32 v14, a204
	s_waitcnt lgkmcnt(0)
	v_mfma_f32_32x32x16_bf16 a[64:79], v[6:9], v[2:5], a[64:79]
	v_mfma_f32_32x32x16_bf16 a[112:127], v[22:25], v[2:5], a[112:127]
	ds_read_b128 v[2:5], v83 offset:64
	ds_read_b128 v[6:9], v84 offset:64
	ds_read_b128 v[10:13], v82 offset:64
	s_waitcnt lgkmcnt(0)
	v_mfma_f32_32x32x16_bf16 a[0:15], v[2:5], v[10:13], a[0:15]
	v_mfma_f32_32x32x16_bf16 a[32:47], v[6:9], v[10:13], a[32:47]
	ds_read_b128 v[10:13], v82 offset:4672
	s_waitcnt lgkmcnt(0)
	v_mfma_f32_32x32x16_bf16 a[16:31], v[2:5], v[10:13], a[16:31]
	v_mfma_f32_32x32x16_bf16 a[80:95], v[6:9], v[10:13], a[80:95]
	ds_read_b128 v[10:13], v82 offset:9280
	s_waitcnt lgkmcnt(0)
	v_mfma_f32_32x32x16_bf16 a[48:63], v[2:5], v[10:13], a[48:63]
	v_mfma_f32_32x32x16_bf16 a[96:111], v[6:9], v[10:13], a[96:111]
	ds_read_b128 v[10:13], v82 offset:13888
	s_waitcnt lgkmcnt(0)
	v_mfma_f32_32x32x16_bf16 a[64:79], v[2:5], v[10:13], a[64:79]
	v_mfma_f32_32x32x16_bf16 a[112:127], v[6:9], v[10:13], a[112:127]
	ds_read_b128 v[2:5], v83 offset:96
	ds_read_b128 v[6:9], v84 offset:96
	ds_read_b128 v[10:13], v82 offset:96
	s_waitcnt lgkmcnt(0)
	v_mfma_f32_32x32x16_bf16 a[0:15], v[2:5], v[10:13], a[0:15]
	v_mfma_f32_32x32x16_bf16 a[32:47], v[6:9], v[10:13], a[32:47]
	ds_read_b128 v[10:13], v82 offset:4704
	s_waitcnt lgkmcnt(0)
	v_mfma_f32_32x32x16_bf16 a[16:31], v[2:5], v[10:13], a[16:31]
	v_mfma_f32_32x32x16_bf16 a[80:95], v[6:9], v[10:13], a[80:95]
	ds_read_b128 v[10:13], v82 offset:9312
	s_waitcnt lgkmcnt(0)
	v_mfma_f32_32x32x16_bf16 a[48:63], v[2:5], v[10:13], a[48:63]
	v_mfma_f32_32x32x16_bf16 a[96:111], v[6:9], v[10:13], a[96:111]
	ds_read_b128 v[10:13], v82 offset:13920
	s_waitcnt lgkmcnt(0)
	v_mfma_f32_32x32x16_bf16 a[64:79], v[2:5], v[10:13], a[64:79]
	v_ashrrev_i32_e32 v3, 31, v0
	v_or_b32_e32 v2, v0, v1
	v_lshl_add_u64 v[0:1], s[0:1], 0, v[2:3]
	v_lshlrev_b64 v[0:1], 12, v[0:1]
	v_accvgpr_read_b32 v2, a177
	v_accvgpr_read_b32 v3, a176
	v_lshl_add_u64 v[0:1], s[10:11], 0, v[0:1]
	v_cvt_pk_bf16_f32 v2, v3, v2
	v_accvgpr_read_b32 v3, a179
	v_accvgpr_read_b32 v4, a178
	v_cvt_pk_bf16_f32 v3, v4, v3
	v_lshl_add_u64 v[0:1], v[0:1], 0, v[248:249]
	global_store_dwordx2 v[0:1], v[2:3], off
	v_accvgpr_read_b32 v2, a181
	v_accvgpr_read_b32 v3, a180
	v_cvt_pk_bf16_f32 v2, v3, v2
	v_accvgpr_read_b32 v3, a183
	v_accvgpr_read_b32 v4, a182
	v_cvt_pk_bf16_f32 v3, v4, v3
	global_store_dwordx2 v[0:1], v[2:3], off offset:16
	v_accvgpr_read_b32 v2, a185
	v_accvgpr_read_b32 v3, a184
	v_cvt_pk_bf16_f32 v2, v3, v2
	v_accvgpr_read_b32 v3, a187
	v_accvgpr_read_b32 v4, a186
	v_cvt_pk_bf16_f32 v3, v4, v3
	global_store_dwordx2 v[0:1], v[2:3], off offset:32
	v_accvgpr_read_b32 v2, a189
	v_accvgpr_read_b32 v3, a188
	v_cvt_pk_bf16_f32 v2, v3, v2
	v_accvgpr_read_b32 v3, a191
	v_accvgpr_read_b32 v4, a190
	v_cvt_pk_bf16_f32 v3, v4, v3
	global_store_dwordx2 v[0:1], v[2:3], off offset:48
	v_accvgpr_read_b32 v2, a161
	v_accvgpr_read_b32 v3, a160
	v_cvt_pk_bf16_f32 v2, v3, v2
	v_accvgpr_read_b32 v3, a163
	v_accvgpr_read_b32 v4, a162
	v_cvt_pk_bf16_f32 v3, v4, v3
	global_store_dwordx2 v[0:1], v[2:3], off offset:64
	v_accvgpr_read_b32 v2, a165
	v_accvgpr_read_b32 v3, a164
	v_cvt_pk_bf16_f32 v2, v3, v2
	v_accvgpr_read_b32 v3, a167
	v_accvgpr_read_b32 v4, a166
	v_cvt_pk_bf16_f32 v3, v4, v3
	global_store_dwordx2 v[0:1], v[2:3], off offset:80
	v_accvgpr_read_b32 v2, a169
	v_accvgpr_read_b32 v3, a168
	v_cvt_pk_bf16_f32 v2, v3, v2
	v_accvgpr_read_b32 v3, a171
	v_accvgpr_read_b32 v4, a170
	v_cvt_pk_bf16_f32 v3, v4, v3
	global_store_dwordx2 v[0:1], v[2:3], off offset:96
	v_accvgpr_read_b32 v2, a173
	v_accvgpr_read_b32 v3, a172
	v_cvt_pk_bf16_f32 v2, v3, v2
	v_accvgpr_read_b32 v3, a175
	v_accvgpr_read_b32 v4, a174
	v_cvt_pk_bf16_f32 v3, v4, v3
	global_store_dwordx2 v[0:1], v[2:3], off offset:112
	v_accvgpr_read_b32 v2, a145
	v_accvgpr_read_b32 v3, a144
	v_cvt_pk_bf16_f32 v2, v3, v2
	v_accvgpr_read_b32 v3, a147
	v_accvgpr_read_b32 v4, a146
	v_cvt_pk_bf16_f32 v3, v4, v3
	global_store_dwordx2 v[0:1], v[2:3], off offset:128
	v_accvgpr_read_b32 v2, a149
	v_accvgpr_read_b32 v3, a148
	v_cvt_pk_bf16_f32 v2, v3, v2
	v_accvgpr_read_b32 v3, a151
	v_accvgpr_read_b32 v4, a150
	v_cvt_pk_bf16_f32 v3, v4, v3
	global_store_dwordx2 v[0:1], v[2:3], off offset:144
	v_accvgpr_read_b32 v2, a153
	v_accvgpr_read_b32 v3, a152
	v_cvt_pk_bf16_f32 v2, v3, v2
	v_accvgpr_read_b32 v3, a155
	v_accvgpr_read_b32 v4, a154
	v_cvt_pk_bf16_f32 v3, v4, v3
	global_store_dwordx2 v[0:1], v[2:3], off offset:160
	v_accvgpr_read_b32 v2, a157
	v_accvgpr_read_b32 v3, a156
	v_cvt_pk_bf16_f32 v2, v3, v2
	v_accvgpr_read_b32 v3, a159
	v_accvgpr_read_b32 v4, a158
	v_cvt_pk_bf16_f32 v3, v4, v3
	global_store_dwordx2 v[0:1], v[2:3], off offset:176
	v_accvgpr_read_b32 v2, a129
	v_accvgpr_read_b32 v3, a128
	v_cvt_pk_bf16_f32 v2, v3, v2
	v_accvgpr_read_b32 v3, a131
	v_accvgpr_read_b32 v4, a130
	v_cvt_pk_bf16_f32 v3, v4, v3
	global_store_dwordx2 v[0:1], v[2:3], off offset:192
	v_accvgpr_read_b32 v2, a133
	v_accvgpr_read_b32 v3, a132
	v_cvt_pk_bf16_f32 v2, v3, v2
	v_accvgpr_read_b32 v3, a135
	v_accvgpr_read_b32 v4, a134
	v_cvt_pk_bf16_f32 v3, v4, v3
	global_store_dwordx2 v[0:1], v[2:3], off offset:208
	v_accvgpr_read_b32 v2, a137
	v_accvgpr_read_b32 v3, a136
	v_cvt_pk_bf16_f32 v2, v3, v2
	v_accvgpr_read_b32 v3, a139
	v_accvgpr_read_b32 v4, a138
	v_cvt_pk_bf16_f32 v3, v4, v3
	global_store_dwordx2 v[0:1], v[2:3], off offset:224
	v_accvgpr_read_b32 v2, a141
	v_accvgpr_read_b32 v3, a140
	v_cvt_pk_bf16_f32 v2, v3, v2
	v_accvgpr_read_b32 v3, a143
	v_accvgpr_read_b32 v4, a142
	v_cvt_pk_bf16_f32 v3, v4, v3
	global_store_dwordx2 v[0:1], v[2:3], off offset:240
	v_accvgpr_read_b32 v0, a1
	v_accvgpr_read_b32 v1, a0
	v_cvt_pk_bf16_f32 v0, v1, v0
	v_accvgpr_read_b32 v1, a3
	v_accvgpr_read_b32 v2, a2
	v_cvt_pk_bf16_f32 v1, v2, v1
	v_accvgpr_read_b32 v2, a5
	v_accvgpr_read_b32 v3, a4
	v_cvt_pk_bf16_f32 v2, v3, v2
	v_accvgpr_read_b32 v3, a7
	v_accvgpr_read_b32 v4, a6
	v_cvt_pk_bf16_f32 v3, v4, v3
	ds_write2_b64 v14, v[0:1], v[2:3] offset1:2
	v_accvgpr_read_b32 v0, a9
	v_accvgpr_read_b32 v1, a8
	v_cvt_pk_bf16_f32 v0, v1, v0
	v_accvgpr_read_b32 v1, a11
	v_accvgpr_read_b32 v2, a10
	v_cvt_pk_bf16_f32 v1, v2, v1
	v_accvgpr_read_b32 v2, a13
	v_accvgpr_read_b32 v3, a12
	v_cvt_pk_bf16_f32 v2, v3, v2
	v_accvgpr_read_b32 v3, a15
	v_accvgpr_read_b32 v4, a14
	v_cvt_pk_bf16_f32 v3, v4, v3
	ds_write2_b64 v14, v[0:1], v[2:3] offset0:4 offset1:6
	v_accvgpr_read_b32 v0, a17
	v_accvgpr_read_b32 v1, a16
	v_cvt_pk_bf16_f32 v0, v1, v0
	v_accvgpr_read_b32 v1, a19
	v_accvgpr_read_b32 v2, a18
	v_cvt_pk_bf16_f32 v1, v2, v1
	v_accvgpr_read_b32 v2, a21
	v_accvgpr_read_b32 v3, a20
	v_cvt_pk_bf16_f32 v2, v3, v2
	v_accvgpr_read_b32 v3, a23
	v_accvgpr_read_b32 v4, a22
	v_cvt_pk_bf16_f32 v3, v4, v3
	v_add_u32_e32 v4, 0x4000, v14
	ds_write2_b64 v4, v[0:1], v[2:3] offset0:64 offset1:66
	v_accvgpr_read_b32 v0, a25
	v_accvgpr_read_b32 v1, a24
	v_cvt_pk_bf16_f32 v0, v1, v0
	v_accvgpr_read_b32 v1, a27
	v_accvgpr_read_b32 v2, a26
	v_cvt_pk_bf16_f32 v1, v2, v1
	v_accvgpr_read_b32 v2, a29
	v_accvgpr_read_b32 v3, a28
	v_cvt_pk_bf16_f32 v2, v3, v2
	v_accvgpr_read_b32 v3, a31
	v_accvgpr_read_b32 v5, a30
	v_cvt_pk_bf16_f32 v3, v5, v3
	ds_write2_b64 v4, v[0:1], v[2:3] offset0:68 offset1:70
	v_accvgpr_read_b32 v0, a49
	v_accvgpr_read_b32 v1, a48
	v_cvt_pk_bf16_f32 v0, v1, v0
	v_accvgpr_read_b32 v1, a51
	v_accvgpr_read_b32 v2, a50
	v_cvt_pk_bf16_f32 v1, v2, v1
	v_accvgpr_read_b32 v2, a53
	v_accvgpr_read_b32 v3, a52
	v_cvt_pk_bf16_f32 v2, v3, v2
	v_accvgpr_read_b32 v3, a55
	v_accvgpr_read_b32 v5, a54
	v_cvt_pk_bf16_f32 v3, v5, v3
	v_add_u32_e32 v5, 0x8000, v14
	ds_write2_b64 v5, v[0:1], v[2:3] offset0:128 offset1:130
	v_accvgpr_read_b32 v0, a57
	v_accvgpr_read_b32 v1, a56
	v_cvt_pk_bf16_f32 v0, v1, v0
	v_accvgpr_read_b32 v1, a59
	v_accvgpr_read_b32 v2, a58
	v_cvt_pk_bf16_f32 v1, v2, v1
	v_accvgpr_read_b32 v2, a61
	v_accvgpr_read_b32 v3, a60
	v_mfma_f32_32x32x16_bf16 a[112:127], v[6:9], v[10:13], a[112:127]
	v_cvt_pk_bf16_f32 v2, v3, v2
	v_accvgpr_read_b32 v3, a63
	v_accvgpr_read_b32 v6, a62
	v_cvt_pk_bf16_f32 v3, v6, v3
	ds_write2_b64 v5, v[0:1], v[2:3] offset0:132 offset1:134
	v_accvgpr_read_b32 v0, a65
	v_accvgpr_read_b32 v1, a64
	v_cvt_pk_bf16_f32 v0, v1, v0
	v_accvgpr_read_b32 v1, a67
	v_accvgpr_read_b32 v2, a66
	v_cvt_pk_bf16_f32 v1, v2, v1
	v_accvgpr_read_b32 v2, a69
	v_accvgpr_read_b32 v3, a68
	v_cvt_pk_bf16_f32 v2, v3, v2
	v_accvgpr_read_b32 v3, a71
	v_accvgpr_read_b32 v6, a70
	v_cvt_pk_bf16_f32 v3, v6, v3
	v_add_u32_e32 v6, 0xc000, v14
	ds_write2_b64 v6, v[0:1], v[2:3] offset0:192 offset1:194
	v_accvgpr_read_b32 v0, a73
	v_accvgpr_read_b32 v1, a72
	v_cvt_pk_bf16_f32 v0, v1, v0
	v_accvgpr_read_b32 v1, a75
	v_accvgpr_read_b32 v2, a74
	v_cvt_pk_bf16_f32 v1, v2, v1
	v_accvgpr_read_b32 v2, a77
	v_accvgpr_read_b32 v3, a76
	v_cvt_pk_bf16_f32 v2, v3, v2
	v_accvgpr_read_b32 v3, a79
	v_accvgpr_read_b32 v7, a78
	v_cvt_pk_bf16_f32 v3, v7, v3
	ds_write2_b64 v6, v[0:1], v[2:3] offset0:196 offset1:198
	v_accvgpr_read_b32 v0, a33
	v_accvgpr_read_b32 v1, a32
	v_cvt_pk_bf16_f32 v0, v1, v0
	v_accvgpr_read_b32 v1, a35
	v_accvgpr_read_b32 v2, a34
	v_cvt_pk_bf16_f32 v1, v2, v1
	v_accvgpr_read_b32 v2, a37
	v_accvgpr_read_b32 v3, a36
	v_cvt_pk_bf16_f32 v2, v3, v2
	v_accvgpr_read_b32 v3, a39
	v_accvgpr_read_b32 v7, a38
	v_cvt_pk_bf16_f32 v3, v7, v3
	ds_write2_b64 v14, v[0:1], v[2:3] offset0:8 offset1:10
	v_accvgpr_read_b32 v0, a41
	v_accvgpr_read_b32 v1, a40
	v_cvt_pk_bf16_f32 v0, v1, v0
	v_accvgpr_read_b32 v1, a43
	v_accvgpr_read_b32 v2, a42
	v_cvt_pk_bf16_f32 v1, v2, v1
	v_accvgpr_read_b32 v2, a45
	v_accvgpr_read_b32 v3, a44
	v_cvt_pk_bf16_f32 v2, v3, v2
	v_accvgpr_read_b32 v3, a47
	v_accvgpr_read_b32 v7, a46
	v_cvt_pk_bf16_f32 v3, v7, v3
	ds_write2_b64 v14, v[0:1], v[2:3] offset0:12 offset1:14
	v_accvgpr_read_b32 v0, a81
	v_accvgpr_read_b32 v1, a80
	v_cvt_pk_bf16_f32 v0, v1, v0
	v_accvgpr_read_b32 v1, a83
	v_accvgpr_read_b32 v2, a82
	v_cvt_pk_bf16_f32 v1, v2, v1
	v_accvgpr_read_b32 v2, a85
	v_accvgpr_read_b32 v3, a84
	v_cvt_pk_bf16_f32 v2, v3, v2
	v_accvgpr_read_b32 v3, a87
	v_accvgpr_read_b32 v7, a86
	v_cvt_pk_bf16_f32 v3, v7, v3
	ds_write2_b64 v4, v[0:1], v[2:3] offset0:72 offset1:74
	v_accvgpr_read_b32 v0, a89
	v_accvgpr_read_b32 v1, a88
	v_cvt_pk_bf16_f32 v0, v1, v0
	v_accvgpr_read_b32 v1, a91
	v_accvgpr_read_b32 v2, a90
	v_cvt_pk_bf16_f32 v1, v2, v1
	v_accvgpr_read_b32 v2, a93
	v_accvgpr_read_b32 v3, a92
	v_cvt_pk_bf16_f32 v2, v3, v2
	v_accvgpr_read_b32 v3, a95
	v_accvgpr_read_b32 v7, a94
	v_cvt_pk_bf16_f32 v3, v7, v3
	ds_write2_b64 v4, v[0:1], v[2:3] offset0:76 offset1:78
	v_accvgpr_read_b32 v0, a97
	v_accvgpr_read_b32 v1, a96
	v_cvt_pk_bf16_f32 v0, v1, v0
	v_accvgpr_read_b32 v1, a99
	v_accvgpr_read_b32 v2, a98
	v_cvt_pk_bf16_f32 v1, v2, v1
	v_accvgpr_read_b32 v2, a101
	v_accvgpr_read_b32 v3, a100
	v_cvt_pk_bf16_f32 v2, v3, v2
	v_accvgpr_read_b32 v3, a103
	v_accvgpr_read_b32 v4, a102
	v_cvt_pk_bf16_f32 v3, v4, v3
	ds_write2_b64 v5, v[0:1], v[2:3] offset0:136 offset1:138
	v_accvgpr_read_b32 v0, a105
	v_accvgpr_read_b32 v1, a104
	v_cvt_pk_bf16_f32 v0, v1, v0
	v_accvgpr_read_b32 v1, a107
	v_accvgpr_read_b32 v2, a106
	v_cvt_pk_bf16_f32 v1, v2, v1
	v_accvgpr_read_b32 v2, a109
	v_accvgpr_read_b32 v3, a108
	v_cvt_pk_bf16_f32 v2, v3, v2
	v_accvgpr_read_b32 v3, a111
	v_accvgpr_read_b32 v4, a110
	v_cvt_pk_bf16_f32 v3, v4, v3
	ds_write2_b64 v5, v[0:1], v[2:3] offset0:140 offset1:142
	v_accvgpr_read_b32 v0, a113
	v_accvgpr_read_b32 v1, a112
	v_cvt_pk_bf16_f32 v0, v1, v0
	v_accvgpr_read_b32 v1, a115
	v_accvgpr_read_b32 v2, a114
	v_cvt_pk_bf16_f32 v1, v2, v1
	v_accvgpr_read_b32 v2, a117
	v_accvgpr_read_b32 v3, a116
	v_cvt_pk_bf16_f32 v2, v3, v2
	v_accvgpr_read_b32 v3, a119
	v_accvgpr_read_b32 v4, a118
	v_cvt_pk_bf16_f32 v3, v4, v3
	ds_write2_b64 v6, v[0:1], v[2:3] offset0:200 offset1:202
	v_accvgpr_read_b32 v0, a121
	v_accvgpr_read_b32 v1, a120
	v_cvt_pk_bf16_f32 v0, v1, v0
	v_accvgpr_read_b32 v1, a123
	v_accvgpr_read_b32 v2, a122
	v_cvt_pk_bf16_f32 v1, v2, v1
	v_accvgpr_read_b32 v2, a125
	v_accvgpr_read_b32 v3, a124
	v_cvt_pk_bf16_f32 v2, v3, v2
	v_accvgpr_read_b32 v3, a127
	v_accvgpr_read_b32 v4, a126
	s_mov_b64 s[0:1], 0x40000
	v_cvt_pk_bf16_f32 v3, v4, v3
	v_lshl_add_u64 v[132:133], v[132:133], 0, s[0:1]
	ds_write2_b64 v6, v[0:1], v[2:3] offset0:204 offset1:206
	s_cbranch_scc0 .LBB0_197
	v_readlane_b32 s0, v254, 40
	v_readlane_b32 s1, v254, 41
	s_load_dword s0, s[0:1], 0x0
	v_mov_b32_e32 v251, 0x3727c5ac
	s_waitcnt lgkmcnt(0)
	s_add_i32 s18, s0, s18
	s_cmpk_gt_i32 s18, 0xff
	s_cbranch_scc0 .LBB0_193
